# v50 + NSA selected/window key loops: per-tile barrier replaced by group-local LDS progress flags for t>=1, group 1 skewed s_sleep 10 per loop
# speedup vs baseline: 1.0020x; 1.0020x over previous
; DI void phase_attn_nsa(const Params& P, bf16_t* og, unsigned char* smem, int L, int G) {
;     ...
;       const unsigned long long bal = __ballot(selected);
;       if (j == 0) selL[q] = (unsigned)(bal >> (32 * (lane >> 5)));
;     }
;     __syncthreads();
;     const unsigned sel = selL[r];
;     unsigned selU = sel;
;     selU |= (unsigned)__shfl_xor((int)selU, 1, 64); selU |= (unsigned)__shfl_xor((int)selU, 2, 64); selU |= (unsigned)__shfl_xor((int)selU, 4, 64);
;     selU |= (unsigned)__shfl_xor((int)selU, 8, 64); selU |= (unsigned)__shfl_xor((int)selU, 16, 64);
;     selU = (unsigned)__builtin_amdgcn_readfirstlane((int)selU);
;     tot_store(totL, tid, o0, o1, g0);
;     {
;       const bf16_t* kb = big + NS_KS + (size_t)b * SEQ * 256 + g * 64;
;       const bf16_t* vb = big + NS_VST + (size_t)((b * 4 + g) * 64) * SEQ;
;       float m = NEGF, l = 0.f; o_zero(o0, o1);
;       const int jhi = (t0 + 31) >> 6;
;       KVR R; kv64_fetch(R, kb, 256, vb, SEQ, 0, true, tid);
;       __syncthreads();
;       kv64_store(R, sK, sVt, tid);
;       if (0 < jhi) kv64_fetch(R, kb, 256, vb, SEQ, 64, true, tid);
.LBB0_1340:
	s_and_b64 s[0:1], s[16:17], s[0:1]
	s_or_b64 s[0:1], s[14:15], s[0:1]
	v_cndmask_b32_e64 v0, 0, 1, s[0:1]
	v_cmp_ne_u32_e32 vcc, 0, v0
	s_and_saveexec_b64 s[0:1], s[8:9]
	s_nop 0
	v_lshrrev_b64 v[36:37], v45, vcc
	ds_write_b32 v46, v36 offset:36960
	s_or_b64 exec, exec, s[0:1]
	s_waitcnt lgkmcnt(0)
	s_barrier
	ds_read_b32 v183, v39 offset:36864
	v_xor_b32_e32 v0, 1, v163
	v_cmp_lt_i32_e32 vcc, v0, v165
	v_readlane_b32 s0, v246, 44
	v_lshlrev_b64 v[36:37], 20, v[114:115]
	v_cndmask_b32_e32 v0, v163, v0, vcc
	v_lshlrev_b32_e32 v0, 2, v0
	v_readlane_b32 s1, v246, 45
	s_waitcnt lgkmcnt(0)
	ds_bpermute_b32 v35, v0, v183
	v_lshlrev_b32_e32 v0, 7, v119
	v_lshl_add_u64 v[36:37], s[0:1], 0, v[36:37]
	v_readlane_b32 s0, v246, 46
	v_lshl_add_u64 v[36:37], v[36:37], 0, v[0:1]
	v_lshlrev_b64 v[38:39], 12, v[116:117]
	v_readlane_b32 s1, v246, 47
	v_lshlrev_b32_e32 v0, 9, v169
	v_mov_b32_e32 v141, v1
	v_lshl_add_u64 v[44:45], s[0:1], 0, v[38:39]
	v_lshl_add_u64 v[38:39], v[36:37], 0, v[0:1]
	v_lshlrev_b32_e32 v0, 9, v174
	v_lshl_add_u64 v[46:47], v[36:37], 0, v[0:1]
	v_lshl_add_u64 v[38:39], v[38:39], 0, v[140:141]
	v_lshl_add_u64 v[46:47], v[46:47], 0, v[140:141]
	v_lshlrev_b32_e32 v0, 12, v169
	global_load_dwordx4 v[90:93], v[38:39], off
	global_load_dwordx4 v[94:97], v[46:47], off
	v_lshl_add_u64 v[46:47], v[44:45], 0, v[0:1]
	v_lshlrev_b32_e32 v0, 12, v174
	v_lshl_add_u64 v[44:45], v[44:45], 0, v[0:1]
	v_lshl_add_u64 v[146:147], v[46:47], 0, v[140:141]
	v_lshl_add_u64 v[148:149], v[44:45], 0, v[140:141]
	global_load_dwordx4 v[98:101], v[146:147], off
	global_load_dwordx4 v[102:105], v[148:149], off
	s_waitcnt lgkmcnt(0)
	v_or_b32_e32 v0, v35, v183
	v_xor_b32_e32 v35, 2, v163
	v_cmp_lt_i32_e32 vcc, v35, v165
	v_lshl_add_u32 v180, v42, 4, v153
	v_add_u32_e32 v181, 0x9200, v180
	v_cndmask_b32_e32 v35, v163, v35, vcc
	v_lshlrev_b32_e32 v35, 2, v35
	ds_bpermute_b32 v35, v35, v0
	s_cmp_lt_u32 s44, 2
	s_mov_b32 s8, 0xff61b1e6
	s_waitcnt lgkmcnt(0)
	v_or_b32_e32 v0, v0, v35
	v_xor_b32_e32 v35, 4, v163
	v_cmp_lt_i32_e32 vcc, v35, v165
	s_nop 1
	v_cndmask_b32_e32 v35, v163, v35, vcc
	v_lshlrev_b32_e32 v35, 2, v35
	ds_bpermute_b32 v35, v35, v0
	s_waitcnt lgkmcnt(0)
	v_or_b32_e32 v0, v0, v35
	v_xor_b32_e32 v35, 8, v163
	v_cmp_lt_i32_e32 vcc, v35, v165
	s_nop 1
	v_cndmask_b32_e32 v35, v163, v35, vcc
	v_lshlrev_b32_e32 v35, 2, v35
	ds_bpermute_b32 v35, v35, v0
	s_waitcnt lgkmcnt(0)
	v_or_b32_e32 v0, v0, v35
	v_xor_b32_e32 v35, 16, v163
	v_cmp_lt_i32_e32 vcc, v35, v165
	s_nop 1
	v_cndmask_b32_e32 v35, v163, v35, vcc
	v_lshlrev_b32_e32 v35, 2, v35
	ds_bpermute_b32 v35, v35, v0
	s_waitcnt lgkmcnt(0)
	v_pk_mul_f32 v[2:3], v[34:35], v[2:3] op_sel_hi:[0,1]
	v_pk_mul_f32 v[4:5], v[34:35], v[4:5] op_sel_hi:[0,1]
	v_pk_mul_f32 v[18:19], v[34:35], v[18:19] op_sel_hi:[0,1]
	v_pk_mul_f32 v[20:21], v[34:35], v[20:21] op_sel_hi:[0,1]
	ds_write_b128 v180, v[2:5] offset:37376
	ds_write_b128 v180, v[18:21] offset:53760
	v_pk_mul_f32 v[2:3], v[34:35], v[6:7] op_sel_hi:[0,1]
	v_pk_mul_f32 v[4:5], v[34:35], v[8:9] op_sel_hi:[0,1]
	v_or_b32_e32 v0, v0, v35
	v_pk_mul_f32 v[6:7], v[34:35], v[22:23] op_sel_hi:[0,1]
	v_pk_mul_f32 v[8:9], v[34:35], v[24:25] op_sel_hi:[0,1]
	ds_write_b128 v180, v[2:5] offset:41472
	ds_write_b128 v180, v[6:9] offset:57856
	v_pk_mul_f32 v[2:3], v[34:35], v[10:11] op_sel_hi:[0,1]
	v_pk_mul_f32 v[4:5], v[34:35], v[12:13] op_sel_hi:[0,1]
	v_readfirstlane_b32 s2, v0
	v_pk_mul_f32 v[6:7], v[34:35], v[26:27] op_sel_hi:[0,1]
	v_pk_mul_f32 v[8:9], v[34:35], v[28:29] op_sel_hi:[0,1]
	ds_write_b128 v180, v[2:5] offset:45568
	ds_write_b128 v180, v[6:9] offset:61952
	v_pk_mul_f32 v[2:3], v[34:35], v[14:15] op_sel_hi:[0,1]
	v_pk_mul_f32 v[4:5], v[34:35], v[16:17] op_sel_hi:[0,1]
	v_pk_mul_f32 v[6:7], v[34:35], v[30:31] op_sel_hi:[0,1]
	v_pk_mul_f32 v[8:9], v[34:35], v[32:33] op_sel_hi:[0,1]
	ds_write_b128 v180, v[2:5] offset:49664
	ds_write_b128 v181, v[6:9] offset:28672
	s_waitcnt lgkmcnt(0)
	v_lshrrev_b32_e32 v250, 8, v192
	v_bfe_u32 v252, v192, 6, 2
	v_and_b32_e32 v251, 7, v192
	v_lshlrev_b32_e32 v250, 6, v250
	v_lshl_add_u32 v252, v252, 2, v250
	v_lshl_add_u32 v250, v251, 2, v250
	v_add_u32_e32 v252, 0x24800, v252
	v_add_u32_e32 v250, 0x24800, v250
	v_mov_b32_e32 v254, 0
	s_mov_b32 s99, 0
	s_barrier
	s_mov_b64 s[100:101], exec
	s_mov_b64 exec, 1
	ds_write_b32 v252, v254
	ds_write_b32 v252, v254 offset:16
	s_mov_b64 exec, s[100:101]
	s_waitcnt vmcnt(3)
	ds_write_b128 v170, v[90:93]
	s_waitcnt vmcnt(2)
	ds_write_b128 v170, v[94:97] offset:4608
	s_waitcnt vmcnt(1)
	ds_write_b128 v170, v[98:101] offset:9216
	s_waitcnt vmcnt(0)
	ds_write_b128 v170, v[102:105] offset:13824
	s_cbranch_scc1 .LBB0_1344
	v_add_co_u32_e32 v2, vcc, 0x8000, v38
	s_nop 1
	v_addc_co_u32_e32 v3, vcc, 0, v39, vcc
	v_add_co_u32_e32 v4, vcc, 0xc000, v38
	s_nop 1
	v_addc_co_u32_e32 v5, vcc, 0, v39, vcc
	global_load_dwordx4 v[90:93], v[2:3], off
	global_load_dwordx4 v[94:97], v[4:5], off
	global_load_dwordx4 v[98:101], v[146:147], off offset:128
	global_load_dwordx4 v[102:105], v[148:149], off offset:128

; DI void phase_attn_nsa(const Params& P, bf16_t* og, unsigned char* smem, int L, int G) {
;     ...
;       for (int j = 0; j <= jhi; ++j) {
;         const int key0 = j * 64, cb = j & 1;
;         __syncthreads();
;         if (j < jhi) kv64_store(R, sK + (cb ^ 1) * KVB64, sVt + (cb ^ 1) * KVB64, tid);
;         if (j + 1 < jhi) kv64_fetch(R, kb, 256, vb, SEQ, key0 + 128, true, tid);
.LBB0_1345:
	s_and_b32 s5, s0, 1
	s_add_i32 s98, s0, 1
	v_mov_b32_e32 v254, s98
	s_cmp_eq_u32 s0, 0
	s_cbranch_scc0 .Lmy_nsasel_spin
	s_waitcnt lgkmcnt(0)
	s_barrier
	v_readfirstlane_b32 s100, v192
	s_cmp_lt_u32 s100, 0x100
	s_cbranch_scc1 .Lmy_nsasel_go
	s_sleep 10
	s_branch .Lmy_nsasel_go
.Lmy_nsasel_spin:
	ds_read_b32 v251, v250
	s_waitcnt lgkmcnt(0)
	v_cmp_gt_u32_e32 vcc, s0, v251
	s_cbranch_vccz .Lmy_nsasel_go
	s_add_i32 s99, s99, 1
	s_cmp_lt_u32 s99, 0x2000
	s_cbranch_scc1 .Lmy_nsasel_spin
.Lmy_nsasel_go:
	s_cmp_ge_u32 s0, s20
	s_cbranch_scc1 .LBB0_1347
	s_xor_b32 s1, s5, 1
	s_mulk_i32 s1, 0x4800
	v_add_u32_e32 v0, s1, v170
	s_waitcnt vmcnt(3)
	ds_write_b128 v0, v[90:93]
	s_waitcnt vmcnt(2)
	ds_write_b128 v0, v[94:97] offset:4608
	s_waitcnt vmcnt(1)
	ds_write_b128 v0, v[98:101] offset:9216
	s_waitcnt vmcnt(0)
	ds_write_b128 v0, v[102:105] offset:13824
	s_mov_b64 s[100:101], exec
	s_mov_b64 exec, 1
	ds_write_b32 v252, v254 offset:16
	s_mov_b64 exec, s[100:101]

; template <int DQK, bool MASKED, int MODE, class MF>
; DI void attn_step(const bf16_t* sK, const bf16_t* sVt, const bf16x8 (&qf)[DQK / 16], f32x16& o0, f32x16& o1, float& m, float& l,
;                   float sc, const MF& mf, int lane, f32x16 (&s)[2], float invl, bool lanevalid = true) {
;   const int r = lane & 31, h = lane >> 5;
;   const int pr = kperm(r);
;   constexpr int KST = DQK + 8;
;   bf16x8 kf[2][DQK / 16];
; #pragma unroll
;   for (int sub = 0; sub < 2; ++sub)
; #pragma unroll
;     for (int ks = 0; ks < DQK / 16; ++ks) kf[sub][ks] = *(const bf16x8*)(sK + (sub * 32 + pr) * KST + ks * 16 + 8 * h);
;   __builtin_amdgcn_sched_barrier(0);
; #pragma unroll
;   for (int q = 0; q < 16; ++q) { s[0][q] = 0.f; s[1][q] = 0.f; }
; #pragma unroll
;   for (int ks = 0; ks < DQK / 16; ++ks) {
;     s[0] = MFMA(kf[0][ks], qf[ks], s[0]);
;     s[1] = MFMA(kf[1][ks], qf[ks], s[1]);
;   }
;   bf16x8 vf[2][2][2];
;   if (MODE != 1) {
; #pragma unroll
;     for (int sub = 0; sub < 2; ++sub)
; #pragma unroll
;       for (int s2 = 0; s2 < 2; ++s2) {
;         vf[sub][s2][0] = *(const bf16x8*)(sVt + r * 72 + sub * 32 + s2 * 16 + 8 * h);
;         vf[sub][s2][1] = *(const bf16x8*)(sVt + (32 + r) * 72 + sub * 32 + s2 * 16 + 8 * h);
;       }
;     __builtin_amdgcn_sched_barrier(0);
;   }
;   float mxr = -3.0e38f;
; #pragma unroll
;   for (int sub = 0; sub < 2; ++sub)
; #pragma unroll
;     for (int q = 0; q < 16; ++q) {
;       if (MASKED) { const int kk = sub * 32 + 16 * (q >> 3) + 8 * h + (q & 7); s[sub][q] = mf(kk) ? s[sub][q] : -3.0e38f; }
;       if (MODE != 2) mxr = fmaxf(mxr, s[sub][q]);
;     }
;   float alpha = 1.f;
;   if (MODE != 2) {
;     float mx = fmaxf(m, mxr * sc);
;     mx = fmaxf(mx, shx(mx, 32));
;     if (!MASKED) mx = lanevalid ? mx : m;
;     alpha = fexp2(m - mx);
;     m = mx;
;   }
;   const float moff = (!MASKED && !lanevalid) ? 1.0e30f : m;
; DI void phase_attn_nsa(const Params& P, bf16_t* og, unsigned char* smem, int L, int G) {
;     ...
;         if ((selU >> j) & 1u) {
;           const bool lsel = (sel >> j) & 1u;
;           auto mf = [&](int kk) { return lsel && (key0 + kk <= t); };
;           if (key0 + 63 > t0) attn_step<64, true, 0>(sK + cb * KVB64, sVt + cb * KVB64, qf, o0, o1, m, l, sc, mf, lane, s, 0.f);
;           else attn_step<64, false, 0>(sK + cb * KVB64, sVt + cb * KVB64, qf, o0, o1, m, l, sc, mf, lane, s, 0.f, lsel);
.LBB0_1349:
	s_lshr_b32 s1, s2, s0
	s_bitcmp0_b32 s1, 0
	s_cbranch_scc1 .Lmy_nsasel_skip
	v_lshrrev_b32_e32 v0, s0, v183
	s_add_i32 s6, s44, 63
	s_mulk_i32 s5, 0x4800
	v_and_b32_e32 v190, 1, v0
	s_mov_b64 s[0:1], -1
	s_cmp_le_u32 s6, s46
	v_max_f32_e32 v188, v141, v141
	v_add_u32_e32 v189, s5, v153
	v_cmp_eq_u32_e32 vcc, 1, v190
	s_cbranch_scc0 .LBB0_1352
	v_add_u32_e32 v0, s5, v182
	ds_read_b128 v[34:37], v0
	ds_read_b128 v[38:41], v0 offset:32
	ds_read_b128 v[106:109], v0 offset:64
	ds_read_b128 v[110:113], v0 offset:96
	ds_read_b128 v[42:45], v0 offset:4608
	ds_read_b128 v[114:117], v0 offset:4640
	ds_read_b128 v[118:121], v0 offset:4672
	ds_read_b128 v[194:197], v0 offset:4704
	s_waitcnt lgkmcnt(7)
	v_mfma_f32_32x32x16_bf16 v[58:73], v[34:37], v[74:77], 0
	v_add3_u32 v0, v189, v175, v138
	v_add3_u32 v34, v189, v177, v138
	s_waitcnt lgkmcnt(3)
	v_mfma_f32_32x32x16_bf16 v[42:57], v[42:45], v[74:77], 0
	v_mfma_f32_32x32x16_bf16 v[58:73], v[38:41], v[78:81], v[58:73]
	s_waitcnt lgkmcnt(2)
	v_mfma_f32_32x32x16_bf16 v[42:57], v[114:117], v[78:81], v[42:57]
	v_mfma_f32_32x32x16_bf16 v[58:73], v[106:109], v[82:85], v[58:73]
	s_waitcnt lgkmcnt(1)
	v_mfma_f32_32x32x16_bf16 v[42:57], v[118:121], v[82:85], v[42:57]
	v_mfma_f32_32x32x16_bf16 v[58:73], v[110:113], v[86:89], v[58:73]
	ds_read_b128 v[198:201], v0 offset:9216
	ds_read_b128 v[126:129], v0 offset:9248
	ds_read_b128 v[130:133], v34 offset:9216
	ds_read_b128 v[122:125], v34 offset:9248
	ds_read_b128 v[118:121], v0 offset:9280
	ds_read_b128 v[110:113], v0 offset:9312
	ds_read_b128 v[114:117], v34 offset:9280
	ds_read_b128 v[106:109], v34 offset:9312
	s_waitcnt lgkmcnt(8)
	v_mfma_f32_32x32x16_bf16 v[42:57], v[194:197], v[86:89], v[42:57]
	s_nop 1
	v_max3_f32 v0, v58, s8, v59
	v_max3_f32 v0, v0, v60, v61
	v_max3_f32 v0, v0, v62, v63
	v_max3_f32 v0, v0, v64, v65
	v_max3_f32 v0, v0, v66, v67
	v_max3_f32 v0, v0, v68, v69
	v_max3_f32 v0, v0, v70, v71
	v_max3_f32 v0, v0, v72, v73
	s_nop 1
	v_max3_f32 v0, v0, v42, v43
	v_max3_f32 v0, v0, v44, v45
	v_max3_f32 v0, v0, v46, v47
	v_max3_f32 v0, v0, v48, v49
	v_max3_f32 v0, v0, v50, v51
	v_max3_f32 v0, v0, v52, v53
	v_max3_f32 v0, v0, v54, v55
	v_max3_f32 v0, v0, v56, v57
	v_mul_f32_e32 v0, 0x3e38aa3b, v0
	v_max_f32_e32 v0, v188, v0
	ds_bpermute_b32 v34, v173, v0
	s_mov_b64 s[0:1], 0
	s_waitcnt lgkmcnt(0)
	s_mov_b64 s[100:101], exec
	s_mov_b64 exec, 1
	ds_write_b32 v252, v254
	s_mov_b64 exec, s[100:101]
	v_max_f32_e32 v34, v34, v34
	v_max_f32_e32 v34, v0, v34
	v_cndmask_b32_e64 v191, v167, -v34, vcc
	v_fmamk_f32 v35, v58, 0x3e38aa3b, v191
	v_fmamk_f32 v36, v59, 0x3e38aa3b, v191
	v_exp_f32_e32 v58, v35
	v_fmamk_f32 v37, v60, 0x3e38aa3b, v191
	v_exp_f32_e32 v59, v36
	v_exp_f32_e32 v60, v37
	v_fmamk_f32 v35, v61, 0x3e38aa3b, v191
	v_exp_f32_e32 v61, v35
	v_add_f32_e32 v36, 0, v58
	v_fmamk_f32 v35, v62, 0x3e38aa3b, v191
	v_add_f32_e32 v36, v59, v36
	v_exp_f32_e32 v62, v35
	v_fmamk_f32 v35, v63, 0x3e38aa3b, v191
	v_add_f32_e32 v36, v60, v36
	v_exp_f32_e32 v63, v35
	v_fmamk_f32 v35, v64, 0x3e38aa3b, v191
	v_exp_f32_e32 v64, v35
	v_add_f32_e32 v35, v61, v36
	v_fmamk_f32 v36, v65, 0x3e38aa3b, v191
	v_exp_f32_e32 v65, v36
	v_fmamk_f32 v36, v66, 0x3e38aa3b, v191
	v_add_f32_e32 v35, v62, v35
	v_exp_f32_e32 v203, v36
	v_fmamk_f32 v36, v67, 0x3e38aa3b, v191
	v_add_f32_e32 v35, v63, v35
	v_exp_f32_e32 v204, v36
	v_fmamk_f32 v36, v68, 0x3e38aa3b, v191
	v_add_f32_e32 v35, v64, v35
	v_exp_f32_e32 v205, v36
	v_fmamk_f32 v36, v69, 0x3e38aa3b, v191
	v_add_f32_e32 v35, v65, v35
	v_exp_f32_e32 v206, v36
	v_fmamk_f32 v36, v70, 0x3e38aa3b, v191
	v_add_f32_e32 v35, v203, v35
	v_exp_f32_e32 v207, v36
	v_fmamk_f32 v36, v71, 0x3e38aa3b, v191
	v_add_f32_e32 v35, v204, v35
	v_exp_f32_e32 v208, v36
	v_fmamk_f32 v36, v72, 0x3e38aa3b, v191
	v_add_f32_e32 v35, v205, v35
	v_exp_f32_e32 v209, v36
	v_fmamk_f32 v36, v73, 0x3e38aa3b, v191
	v_add_f32_e32 v35, v206, v35
	v_exp_f32_e32 v210, v36
	v_fmamk_f32 v36, v42, 0x3e38aa3b, v191
	v_add_f32_e32 v35, v207, v35
	v_exp_f32_e32 v211, v36
	v_fmamk_f32 v36, v43, 0x3e38aa3b, v191
	v_add_f32_e32 v35, v208, v35
	v_exp_f32_e32 v212, v36
	v_fmamk_f32 v36, v44, 0x3e38aa3b, v191
	v_add_f32_e32 v35, v209, v35
	v_exp_f32_e32 v213, v36
	v_fmamk_f32 v36, v45, 0x3e38aa3b, v191
	v_add_f32_e32 v35, v210, v35
	v_exp_f32_e32 v214, v36
	v_fmamk_f32 v36, v46, 0x3e38aa3b, v191
	v_add_f32_e32 v35, v211, v35
	v_exp_f32_e32 v215, v36
	v_fmamk_f32 v36, v47, 0x3e38aa3b, v191
	v_cndmask_b32_e32 v0, v141, v34, vcc
	v_add_f32_e32 v35, v212, v35
	v_exp_f32_e32 v216, v36
	v_fmamk_f32 v36, v48, 0x3e38aa3b, v191
	v_sub_f32_e32 v34, v141, v0
	v_add_f32_e32 v35, v213, v35
	v_exp_f32_e32 v217, v36
	v_add_f32_e32 v35, v214, v35
	v_exp_f32_e32 v202, v34
	v_add_f32_e32 v35, v215, v35
	v_add_f32_e32 v35, v216, v35
	v_add_f32_e32 v218, v217, v35
	v_fmamk_f32 v35, v49, 0x3e38aa3b, v191
	v_fmamk_f32 v34, v50, 0x3e38aa3b, v191
	v_exp_f32_e32 v219, v35
	v_exp_f32_e32 v220, v34
	v_pk_mul_f32 v[48:49], v[32:33], v[202:203] op_sel_hi:[1,0]
	v_pk_mul_f32 v[46:47], v[30:31], v[202:203] op_sel_hi:[1,0]
	v_pk_mul_f32 v[44:45], v[28:29], v[202:203] op_sel_hi:[1,0]
	v_pk_mul_f32 v[42:43], v[26:27], v[202:203] op_sel_hi:[1,0]
	v_pk_mul_f32 v[40:41], v[24:25], v[202:203] op_sel_hi:[1,0]
	v_pk_mul_f32 v[38:39], v[22:23], v[202:203] op_sel_hi:[1,0]
	v_pk_mul_f32 v[36:37], v[20:21], v[202:203] op_sel_hi:[1,0]
	v_pk_mul_f32 v[34:35], v[18:19], v[202:203] op_sel_hi:[1,0]
	v_cvt_pk_bf16_f32 v194, v58, v59
	v_cvt_pk_bf16_f32 v195, v60, v61
	v_cvt_pk_bf16_f32 v196, v62, v63
	v_cvt_pk_bf16_f32 v197, v64, v65
	v_pk_mul_f32 v[72:73], v[16:17], v[202:203] op_sel_hi:[1,0]
	v_pk_mul_f32 v[70:71], v[14:15], v[202:203] op_sel_hi:[1,0]
; #define MFMA(a, b, c) __builtin_amdgcn_mfma_f32_32x32x16_bf16((a), (b), (c), 0, 0, 0)
; DI unsigned pack2(float a, float b) { f32x2_t v = {a, b}; bf16x2_t r = __builtin_convertvector(v, bf16x2_t); return __builtin_bit_cast(unsigned, r); }
; DI float shx(float v, int m) { return __shfl_xor(v, m, 64); }
; template <int DQK, bool MASKED, int MODE, class MF>
; DI void attn_step(const bf16_t* sK, const bf16_t* sVt, const bf16x8 (&qf)[DQK / 16], f32x16& o0, f32x16& o1, float& m, float& l,
;                   float sc, const MF& mf, int lane, f32x16 (&s)[2], float invl, bool lanevalid = true) {
;     ...
;     }
;   if (MODE != 2) {
;     ps += shx(ps, 32);
;     l = l * alpha + ps;
;   }
;   if (MODE == 1) return;
;   if (MODE == 0) {
; #pragma unroll
;     for (int q = 0; q < 16; ++q) { o0[q] *= alpha; o1[q] *= alpha; }
;   }
; #pragma unroll
;   for (int sub = 0; sub < 2; ++sub)
; #pragma unroll
;     for (int s2 = 0; s2 < 2; ++s2) {
;       union { bf16x8 v; unsigned u[4]; } pb;
; #pragma unroll
;       for (int e = 0; e < 4; ++e) pb.u[e] = pack2(s[sub][8 * s2 + 2 * e], s[sub][8 * s2 + 2 * e + 1]);
;       o0 = MFMA(vf[sub][s2][0], pb.v, o0);
;       o1 = MFMA(vf[sub][s2][1], pb.v, o1);
;     }
; }
; DI void phase_attn_nsa(const Params& P, bf16_t* og, unsigned char* smem, int L, int G) {
;     ...
;           if (key0 + 63 > t0) attn_step<64, true, 0>(sK + cb * KVB64, sVt + cb * KVB64, qf, o0, o1, m, l, sc, mf, lane, s, 0.f);
	v_mfma_f32_32x32x16_bf16 v[34:49], v[198:201], v[194:197], v[34:49]
	v_mul_f32_e64 v68, v12, v202
	v_mul_f32_e64 v69, v13, v202
	v_mul_f32_e64 v66, v10, v202
	v_mul_f32_e64 v67, v11, v202
	v_mul_f32_e64 v64, v8, v202
	v_mul_f32_e64 v65, v9, v202
	v_pk_mul_f32 v[62:63], v[6:7], v[202:203] op_sel_hi:[1,0]
	v_pk_mul_f32 v[60:61], v[4:5], v[202:203] op_sel_hi:[1,0]
	v_pk_mul_f32 v[58:59], v[2:3], v[202:203] op_sel_hi:[1,0]
	v_fmamk_f32 v51, v51, 0x3e38aa3b, v191
	v_add_f32_e32 v50, v219, v218
	v_mfma_f32_32x32x16_bf16 v[58:73], v[130:133], v[194:197], v[58:73]
	v_cvt_pk_bf16_f32 v130, v203, v204
	v_cvt_pk_bf16_f32 v131, v205, v206
	v_cvt_pk_bf16_f32 v132, v207, v208
	v_cvt_pk_bf16_f32 v133, v209, v210
	v_add_f32_e32 v50, v220, v50
	v_fmamk_f32 v55, v55, 0x3e38aa3b, v191
	v_exp_f32_e32 v55, v55
	v_mfma_f32_32x32x16_bf16 v[34:49], v[126:129], v[130:133], v[34:49]
	v_exp_f32_e32 v126, v51
	v_fmamk_f32 v51, v52, 0x3e38aa3b, v191
	v_exp_f32_e32 v127, v51
	v_fmamk_f32 v51, v53, 0x3e38aa3b, v191
	v_exp_f32_e32 v128, v51
	v_add_f32_e32 v50, v126, v50
	v_add_f32_e32 v50, v127, v50
	v_mfma_f32_32x32x16_bf16 v[58:73], v[122:125], v[130:133], v[58:73]
	v_add_f32_e32 v122, v128, v50
	v_fmamk_f32 v50, v54, 0x3e38aa3b, v191
	v_exp_f32_e32 v54, v50
	v_fmamk_f32 v56, v56, 0x3e38aa3b, v191
	v_exp_f32_e32 v56, v56
	v_fmac_f32_e32 v191, 0x3e38aa3b, v57
	v_cvt_pk_bf16_f32 v50, v211, v212
	v_cvt_pk_bf16_f32 v51, v213, v214
	v_cvt_pk_bf16_f32 v52, v215, v216
	v_cvt_pk_bf16_f32 v53, v217, v219
	v_exp_f32_e32 v57, v191
	s_nop 0
	v_mfma_f32_32x32x16_bf16 v[34:49], v[118:121], v[50:53], v[34:49]
	v_add_f32_e32 v118, v54, v122
	v_cvt_pk_bf16_f32 v54, v54, v55
	v_mfma_f32_32x32x16_bf16 v[58:73], v[114:117], v[50:53], v[58:73]
	v_add_f32_e32 v50, v55, v118
	v_add_f32_e32 v50, v56, v50
	v_add_f32_e32 v50, v57, v50
	ds_bpermute_b32 v51, v173, v50
	v_cvt_pk_bf16_f32 v52, v220, v126
	v_cvt_pk_bf16_f32 v53, v127, v128
	v_cvt_pk_bf16_f32 v55, v56, v57
	s_waitcnt lgkmcnt(0)
	v_add_f32_e32 v50, v50, v51
	v_mfma_f32_32x32x16_bf16 v[34:49], v[110:113], v[52:55], v[34:49]
	v_fmac_f32_e32 v50, v185, v202
	v_mfma_f32_32x32x16_bf16 v[58:73], v[106:109], v[52:55], v[58:73]
.LBB0_1352:
	s_andn2_b64 vcc, exec, s[0:1]
	s_cbranch_vccnz .LBB0_1354
	v_add_u32_e32 v0, s5, v172
	s_nop 6
	ds_read_b128 v[34:37], v0
	s_nop 0
	ds_read_b128 v[66:69], v0 offset:32
	ds_read_b128 v[70:73], v0 offset:64
	ds_read_b128 v[106:109], v0 offset:96
	ds_read_b128 v[38:41], v0 offset:4608
	ds_read_b128 v[110:113], v0 offset:4640
	ds_read_b128 v[114:117], v0 offset:4672
	ds_read_b128 v[194:197], v0 offset:4704
	v_cmp_eq_u32_e32 vcc, 1, v190
	s_waitcnt lgkmcnt(7)
	v_mfma_f32_32x32x16_bf16 v[50:65], v[34:37], v[74:77], 0
	v_lshlrev_b32_e32 v0, 1, v171
	s_waitcnt lgkmcnt(3)
	v_mfma_f32_32x32x16_bf16 v[34:49], v[38:41], v[74:77], 0
	v_mfma_f32_32x32x16_bf16 v[50:65], v[66:69], v[78:81], v[50:65]
	s_waitcnt lgkmcnt(2)
	v_mfma_f32_32x32x16_bf16 v[34:49], v[110:113], v[78:81], v[34:49]
	v_mfma_f32_32x32x16_bf16 v[50:65], v[70:73], v[82:85], v[50:65]
	v_add3_u32 v70, v189, v175, v0
	v_add3_u32 v0, v189, v177, v0
	s_waitcnt lgkmcnt(1)
	v_mfma_f32_32x32x16_bf16 v[34:49], v[114:117], v[82:85], v[34:49]
	v_mfma_f32_32x32x16_bf16 v[50:65], v[106:109], v[86:89], v[50:65]
	ds_read_b128 v[66:69], v70 offset:9216
	ds_read_b128 v[126:129], v70 offset:9248
	ds_read_b128 v[130:133], v0 offset:9216
	ds_read_b128 v[122:125], v0 offset:9248
	ds_read_b128 v[118:121], v70 offset:9280
	ds_read_b128 v[110:113], v70 offset:9312
	ds_read_b128 v[114:117], v0 offset:9280
	ds_read_b128 v[106:109], v0 offset:9312
	s_waitcnt lgkmcnt(8)
	v_mfma_f32_32x32x16_bf16 v[34:49], v[194:197], v[86:89], v[34:49]
	v_add_u32_e32 v0, s44, v171
	v_cmp_le_u32_e64 s[0:1], v0, v136
	s_and_b64 s[0:1], vcc, s[0:1]
	v_add_u32_e32 v70, 2, v0
	v_cndmask_b32_e64 v50, v166, v50, s[0:1]
	v_cmp_lt_u32_e64 s[0:1], v0, v136
	s_and_b64 s[0:1], vcc, s[0:1]
	s_nop 0
	v_cndmask_b32_e64 v51, v166, v51, s[0:1]
	v_cmp_le_u32_e64 s[0:1], v70, v136
	s_and_b64 s[0:1], vcc, s[0:1]
	v_add_u32_e32 v70, 3, v0
	v_cndmask_b32_e64 v52, v166, v52, s[0:1]
	v_cmp_le_u32_e64 s[0:1], v70, v136
	s_and_b64 s[0:1], vcc, s[0:1]
	v_add_u32_e32 v70, 4, v0
	v_cndmask_b32_e64 v53, v166, v53, s[0:1]
	v_cmp_le_u32_e64 s[0:1], v70, v136
	s_and_b64 s[0:1], vcc, s[0:1]
	v_add_u32_e32 v70, 5, v0
	v_cndmask_b32_e64 v54, v166, v54, s[0:1]
	v_cmp_le_u32_e64 s[0:1], v70, v136
	s_and_b64 s[0:1], vcc, s[0:1]
	v_add_u32_e32 v70, 6, v0
	v_cndmask_b32_e64 v55, v166, v55, s[0:1]
	v_cmp_le_u32_e64 s[0:1], v70, v136
	v_add_u32_e32 v70, s44, v139
	s_and_b64 s[0:1], vcc, s[0:1]
	v_or_b32_e32 v71, 7, v70
	v_cndmask_b32_e64 v56, v166, v56, s[0:1]
	v_cmp_le_u32_e64 s[0:1], v71, v136
	s_and_b64 s[0:1], vcc, s[0:1]
	v_add_u32_e32 v71, 16, v0
	v_cndmask_b32_e64 v57, v166, v57, s[0:1]
	v_cmp_le_u32_e64 s[0:1], v71, v136
	s_and_b64 s[0:1], vcc, s[0:1]
	v_add_u32_e32 v71, 17, v0
	v_cndmask_b32_e64 v58, v166, v58, s[0:1]
	v_cmp_le_u32_e64 s[0:1], v71, v136
	s_and_b64 s[0:1], vcc, s[0:1]
	v_add_u32_e32 v71, 18, v0
	v_cndmask_b32_e64 v59, v166, v59, s[0:1]
	v_cmp_le_u32_e64 s[0:1], v71, v136
	s_and_b64 s[0:1], vcc, s[0:1]
	v_add_u32_e32 v71, 19, v0
	v_cndmask_b32_e64 v60, v166, v60, s[0:1]
	v_cmp_le_u32_e64 s[0:1], v71, v136
	s_and_b64 s[0:1], vcc, s[0:1]
	v_add_u32_e32 v71, 20, v0
	v_cndmask_b32_e64 v61, v166, v61, s[0:1]
	v_cmp_le_u32_e64 s[0:1], v71, v136
	s_and_b64 s[0:1], vcc, s[0:1]
	v_add_u32_e32 v71, 21, v0
	v_cndmask_b32_e64 v62, v166, v62, s[0:1]
	v_cmp_le_u32_e64 s[0:1], v71, v136
	s_and_b64 s[0:1], vcc, s[0:1]
	v_add_u32_e32 v71, 22, v0
	v_cndmask_b32_e64 v63, v166, v63, s[0:1]
	v_cmp_le_u32_e64 s[0:1], v71, v136
; DI float shx(float v, int m) { return __shfl_xor(v, m, 64); }
; template <int DQK, bool MASKED, int MODE, class MF>
; DI void attn_step(const bf16_t* sK, const bf16_t* sVt, const bf16x8 (&qf)[DQK / 16], f32x16& o0, f32x16& o1, float& m, float& l,
;                   float sc, const MF& mf, int lane, f32x16 (&s)[2], float invl, bool lanevalid = true) {
;     ...
;       if (MASKED) { const int kk = sub * 32 + 16 * (q >> 3) + 8 * h + (q & 7); s[sub][q] = mf(kk) ? s[sub][q] : -3.0e38f; }
;       if (MODE != 2) mxr = fmaxf(mxr, s[sub][q]);
;     }
;   float alpha = 1.f;
;   if (MODE != 2) {
;     float mx = fmaxf(m, mxr * sc);
;     mx = fmaxf(mx, shx(mx, 32));
	s_and_b64 s[0:1], vcc, s[0:1]
	v_or_b32_e32 v71, 23, v70
	v_cndmask_b32_e64 v64, v166, v64, s[0:1]
	v_cmp_le_u32_e64 s[0:1], v71, v136
	s_and_b64 s[0:1], vcc, s[0:1]
	v_add_u32_e32 v71, 32, v0
	v_cndmask_b32_e64 v65, v166, v65, s[0:1]
	v_cmp_le_u32_e64 s[0:1], v71, v136
	s_and_b64 s[0:1], vcc, s[0:1]
	v_add_u32_e32 v71, 33, v0
	v_cndmask_b32_e64 v34, v166, v34, s[0:1]
	v_cmp_le_u32_e64 s[0:1], v71, v136
	s_and_b64 s[0:1], vcc, s[0:1]
	v_add_u32_e32 v71, 34, v0
	v_cndmask_b32_e64 v35, v166, v35, s[0:1]
	v_cmp_le_u32_e64 s[0:1], v71, v136
	s_and_b64 s[0:1], vcc, s[0:1]
	v_add_u32_e32 v71, 35, v0
	v_cndmask_b32_e64 v36, v166, v36, s[0:1]
	v_cmp_le_u32_e64 s[0:1], v71, v136
	s_and_b64 s[0:1], vcc, s[0:1]
	v_add_u32_e32 v71, 36, v0
	v_cndmask_b32_e64 v37, v166, v37, s[0:1]
	v_cmp_le_u32_e64 s[0:1], v71, v136
	s_and_b64 s[0:1], vcc, s[0:1]
	v_add_u32_e32 v71, 37, v0
	v_cndmask_b32_e64 v38, v166, v38, s[0:1]
	v_cmp_le_u32_e64 s[0:1], v71, v136
	s_and_b64 s[0:1], vcc, s[0:1]
	v_add_u32_e32 v71, 38, v0
	v_cndmask_b32_e64 v39, v166, v39, s[0:1]
	v_cmp_le_u32_e64 s[0:1], v71, v136
	s_and_b64 s[0:1], vcc, s[0:1]
	v_or_b32_e32 v71, 39, v70
	v_cndmask_b32_e64 v40, v166, v40, s[0:1]
	v_cmp_le_u32_e64 s[0:1], v71, v136
	s_and_b64 s[0:1], vcc, s[0:1]
	v_add_u32_e32 v71, 48, v0
	v_cndmask_b32_e64 v41, v166, v41, s[0:1]
	v_cmp_le_u32_e64 s[0:1], v71, v136
	s_and_b64 s[0:1], vcc, s[0:1]
	v_add_u32_e32 v71, 49, v0
	v_cndmask_b32_e64 v42, v166, v42, s[0:1]
	v_cmp_le_u32_e64 s[0:1], v71, v136
	s_and_b64 s[0:1], vcc, s[0:1]
	s_nop 0
	v_cndmask_b32_e64 v189, v166, v43, s[0:1]
	v_add_u32_e32 v43, 50, v0
	v_cmp_le_u32_e64 s[0:1], v43, v136
	s_and_b64 s[0:1], vcc, s[0:1]
	v_add_u32_e32 v43, 51, v0
	v_cndmask_b32_e64 v190, v166, v44, s[0:1]
	v_cmp_le_u32_e64 s[0:1], v43, v136
	s_and_b64 s[0:1], vcc, s[0:1]
	v_add_u32_e32 v43, 52, v0
	v_cndmask_b32_e64 v191, v166, v45, s[0:1]
	v_cmp_le_u32_e64 s[0:1], v43, v136
	s_and_b64 s[0:1], vcc, s[0:1]
	v_add_u32_e32 v43, 53, v0
	v_cndmask_b32_e64 v194, v166, v46, s[0:1]
	v_cmp_le_u32_e64 s[0:1], v43, v136
	s_and_b64 s[0:1], vcc, s[0:1]
	v_add_u32_e32 v0, 54, v0
	v_cndmask_b32_e64 v195, v166, v47, s[0:1]
	v_cmp_le_u32_e64 s[0:1], v0, v136
	s_and_b64 s[0:1], vcc, s[0:1]
	v_or_b32_e32 v0, 55, v70
	v_cndmask_b32_e64 v196, v166, v48, s[0:1]
	v_cmp_le_u32_e64 s[0:1], v0, v136
	v_max3_f32 v0, v50, s8, v51
	v_max3_f32 v0, v0, v52, v53
	v_max3_f32 v0, v0, v54, v55
	v_max3_f32 v0, v0, v56, v57
	v_max3_f32 v0, v0, v58, v59
	v_max3_f32 v0, v0, v60, v61
	v_max3_f32 v0, v0, v62, v63
	v_max3_f32 v0, v0, v64, v65
	v_max3_f32 v0, v0, v34, v35
	v_max3_f32 v0, v0, v36, v37
	v_max3_f32 v0, v0, v38, v39
	v_max3_f32 v0, v0, v40, v41
	v_max3_f32 v0, v0, v42, v189
	s_and_b64 vcc, vcc, s[0:1]
	v_max3_f32 v0, v0, v190, v191
	v_cndmask_b32_e32 v197, v166, v49, vcc
	v_max3_f32 v0, v0, v194, v195
	v_max3_f32 v0, v0, v196, v197
	v_mul_f32_e32 v0, 0x3e38aa3b, v0
	v_max_f32_e32 v0, v188, v0
	ds_bpermute_b32 v43, v173, v0
	s_waitcnt lgkmcnt(0)
; #define MFMA(a, b, c) __builtin_amdgcn_mfma_f32_32x32x16_bf16((a), (b), (c), 0, 0, 0)
; DI unsigned pack2(float a, float b) { f32x2_t v = {a, b}; bf16x2_t r = __builtin_convertvector(v, bf16x2_t); return __builtin_bit_cast(unsigned, r); }
; DI float fexp2(float x) { return __builtin_amdgcn_exp2f(x); }
; DI float shx(float v, int m) { return __shfl_xor(v, m, 64); }
; template <int DQK, bool MASKED, int MODE, class MF>
; DI void attn_step(const bf16_t* sK, const bf16_t* sVt, const bf16x8 (&qf)[DQK / 16], f32x16& o0, f32x16& o1, float& m, float& l,
;                   float sc, const MF& mf, int lane, f32x16 (&s)[2], float invl, bool lanevalid = true) {
;     ...
;   float alpha = 1.f;
;   if (MODE != 2) {
;     float mx = fmaxf(m, mxr * sc);
;     mx = fmaxf(mx, shx(mx, 32));
;     if (!MASKED) mx = lanevalid ? mx : m;
;     alpha = fexp2(m - mx);
;     m = mx;
;   }
;   const float moff = (!MASKED && !lanevalid) ? 1.0e30f : m;
;   float ps = 0.f;
; #pragma unroll
;   for (int sub = 0; sub < 2; ++sub)
; #pragma unroll
;     for (int q = 0; q < 16; ++q) {
;       float pv = fexp2(__builtin_fmaf(s[sub][q], sc, -moff));
;       if (MASKED && MODE != 0) pv = (s[sub][q] > -1.0e38f) ? pv : 0.f;
;       if (MODE == 2) pv *= invl;
;       s[sub][q] = pv;
;       ps += pv;
;     }
;   if (MODE != 2) {
;     ps += shx(ps, 32);
;     l = l * alpha + ps;
;   }
;   if (MODE == 1) return;
;   if (MODE == 0) {
; #pragma unroll
;     for (int q = 0; q < 16; ++q) { o0[q] *= alpha; o1[q] *= alpha; }
;   }
; #pragma unroll
;   for (int sub = 0; sub < 2; ++sub)
; #pragma unroll
;     for (int s2 = 0; s2 < 2; ++s2) {
;       union { bf16x8 v; unsigned u[4]; } pb;
; #pragma unroll
;       for (int e = 0; e < 4; ++e) pb.u[e] = pack2(s[sub][8 * s2 + 2 * e], s[sub][8 * s2 + 2 * e + 1]);
;       o0 = MFMA(vf[sub][s2][0], pb.v, o0);
;       o1 = MFMA(vf[sub][s2][1], pb.v, o1);
;     }
; }
	s_mov_b64 s[100:101], exec
	s_mov_b64 exec, 1
	ds_write_b32 v252, v254
	s_mov_b64 exec, s[100:101]
	v_max_f32_e32 v43, v43, v43
	v_max_f32_e32 v0, v0, v43
	v_fma_f32 v43, v50, s33, -v0
	v_exp_f32_e32 v50, v43
	v_fma_f32 v43, v51, s33, -v0
	v_exp_f32_e32 v51, v43
	v_fma_f32 v43, v52, s33, -v0
	v_exp_f32_e32 v70, v43
	v_fma_f32 v45, v53, s33, -v0
	v_exp_f32_e32 v53, v45
	v_fma_f32 v45, v54, s33, -v0
	v_add_f32_e32 v44, 0, v50
	v_exp_f32_e32 v54, v45
	v_fma_f32 v45, v55, s33, -v0
	v_add_f32_e32 v44, v51, v44
	v_exp_f32_e32 v55, v45
	v_fma_f32 v45, v56, s33, -v0
	v_add_f32_e32 v44, v70, v44
	v_exp_f32_e32 v56, v45
	v_fma_f32 v45, v57, s33, -v0
	v_add_f32_e32 v44, v53, v44
	v_exp_f32_e32 v57, v45
	v_fma_f32 v45, v58, s33, -v0
	v_sub_f32_e32 v43, v141, v0
	v_add_f32_e32 v44, v54, v44
	v_exp_f32_e32 v141, v45
	v_fma_f32 v45, v59, s33, -v0
	v_add_f32_e32 v44, v55, v44
	v_exp_f32_e32 v188, v45
	v_fma_f32 v45, v60, s33, -v0
	v_add_f32_e32 v44, v56, v44
	v_exp_f32_e32 v198, v45
	v_fma_f32 v45, v61, s33, -v0
	v_add_f32_e32 v44, v57, v44
	v_exp_f32_e32 v199, v45
	v_fma_f32 v45, v62, s33, -v0
	v_add_f32_e32 v44, v141, v44
	v_exp_f32_e32 v200, v45
	v_fma_f32 v45, v63, s33, -v0
	v_add_f32_e32 v44, v188, v44
	v_exp_f32_e32 v201, v45
	v_fma_f32 v45, v64, s33, -v0
	v_add_f32_e32 v44, v198, v44
	v_exp_f32_e32 v202, v45
	v_fma_f32 v45, v65, s33, -v0
	v_add_f32_e32 v44, v199, v44
	v_exp_f32_e32 v203, v45
	v_fma_f32 v34, v34, s33, -v0
	v_add_f32_e32 v44, v200, v44
	v_exp_f32_e32 v204, v34
	v_fma_f32 v34, v35, s33, -v0
	v_add_f32_e32 v44, v201, v44
	v_exp_f32_e32 v205, v34
	v_fma_f32 v34, v36, s33, -v0
	v_add_f32_e32 v44, v202, v44
	v_exp_f32_e32 v206, v34
	v_fma_f32 v35, v37, s33, -v0
	v_add_f32_e32 v34, v203, v44
	v_exp_f32_e32 v207, v35
	v_fma_f32 v35, v38, s33, -v0
	v_add_f32_e32 v34, v204, v34
	v_exp_f32_e32 v208, v35
	v_fma_f32 v35, v39, s33, -v0
	v_add_f32_e32 v34, v205, v34
	v_exp_f32_e32 v209, v35
	v_fma_f32 v35, v40, s33, -v0
	v_add_f32_e32 v34, v206, v34
	v_exp_f32_e32 v210, v35
	v_add_f32_e32 v34, v207, v34
	v_add_f32_e32 v34, v208, v34
	v_exp_f32_e32 v52, v43
	v_add_f32_e32 v34, v209, v34
	v_add_f32_e32 v211, v210, v34
	v_fma_f32 v34, v41, s33, -v0
	v_exp_f32_e32 v212, v34
	v_fma_f32 v34, v42, s33, -v0
	v_exp_f32_e32 v213, v34
	v_pk_mul_f32 v[48:49], v[32:33], v[52:53] op_sel_hi:[1,0]
	v_pk_mul_f32 v[46:47], v[30:31], v[52:53] op_sel_hi:[1,0]
	v_pk_mul_f32 v[44:45], v[28:29], v[52:53] op_sel_hi:[1,0]
	v_pk_mul_f32 v[42:43], v[26:27], v[52:53] op_sel_hi:[1,0]
	v_pk_mul_f32 v[40:41], v[24:25], v[52:53] op_sel_hi:[1,0]
	v_pk_mul_f32 v[38:39], v[22:23], v[52:53] op_sel_hi:[1,0]
	v_pk_mul_f32 v[36:37], v[20:21], v[52:53] op_sel_hi:[1,0]
	v_pk_mul_f32 v[34:35], v[18:19], v[52:53] op_sel_hi:[1,0]
	v_pk_mul_f32 v[72:73], v[16:17], v[52:53] op_sel_hi:[1,0]
	v_cvt_pk_bf16_f32 v16, v50, v51
	v_cvt_pk_bf16_f32 v17, v70, v53
	v_cvt_pk_bf16_f32 v18, v54, v55
	v_cvt_pk_bf16_f32 v19, v56, v57
	v_pk_mul_f32 v[70:71], v[14:15], v[52:53] op_sel_hi:[1,0]
	v_pk_mul_f32 v[64:65], v[8:9], v[52:53] op_sel_hi:[1,0]
	v_mfma_f32_32x32x16_bf16 v[34:49], v[66:69], v[16:19], v[34:49]
	v_mul_f32_e64 v68, v12, v52
	v_mul_f32_e64 v69, v13, v52
	v_mul_f32_e64 v66, v10, v52
	v_mul_f32_e64 v67, v11, v52
	v_mul_f32_e64 v62, v6, v52
	v_mul_f32_e64 v63, v7, v52
	v_pk_mul_f32 v[60:61], v[4:5], v[52:53] op_sel_hi:[1,0]
	v_pk_mul_f32 v[58:59], v[2:3], v[52:53] op_sel_hi:[1,0]
	v_add_f32_e32 v2, v212, v211
	v_add_f32_e32 v6, v213, v2
	v_mfma_f32_32x32x16_bf16 v[58:73], v[130:133], v[16:19], v[58:73]
	v_cvt_pk_bf16_f32 v2, v141, v188
	v_cvt_pk_bf16_f32 v3, v198, v199
	v_cvt_pk_bf16_f32 v4, v200, v201
	v_cvt_pk_bf16_f32 v5, v202, v203
	v_fma_f32 v7, v189, s33, -v0
	v_exp_f32_e32 v7, v7
	v_fma_f32 v8, v190, s33, -v0
	v_mfma_f32_32x32x16_bf16 v[34:49], v[126:129], v[2:5], v[34:49]
	v_exp_f32_e32 v8, v8
	v_fma_f32 v9, v191, s33, -v0
	v_exp_f32_e32 v9, v9
	v_fma_f32 v11, v195, s33, -v0
	v_add_f32_e32 v6, v7, v6
	v_exp_f32_e32 v11, v11
	v_fma_f32 v12, v196, s33, -v0
	v_mfma_f32_32x32x16_bf16 v[58:73], v[122:125], v[2:5], v[58:73]
	v_fma_f32 v2, v194, s33, -v0
	v_exp_f32_e32 v10, v2
	v_cvt_pk_bf16_f32 v2, v204, v205
	v_cvt_pk_bf16_f32 v3, v206, v207
	v_cvt_pk_bf16_f32 v4, v208, v209
	v_cvt_pk_bf16_f32 v5, v210, v212
	v_add_f32_e32 v6, v8, v6
	v_exp_f32_e32 v12, v12
	v_mfma_f32_32x32x16_bf16 v[34:49], v[118:121], v[2:5], v[34:49]
	v_fma_f32 v13, v197, s33, -v0
	v_add_f32_e32 v6, v9, v6
	v_exp_f32_e32 v13, v13
	v_add_f32_e32 v6, v10, v6
	v_mfma_f32_32x32x16_bf16 v[58:73], v[114:117], v[2:5], v[58:73]
	v_add_f32_e32 v2, v11, v6
	v_add_f32_e32 v2, v12, v2
	v_add_f32_e32 v6, v13, v2
	v_cvt_pk_bf16_f32 v2, v213, v7
	v_cvt_pk_bf16_f32 v3, v8, v9
	v_cvt_pk_bf16_f32 v4, v10, v11
	v_cvt_pk_bf16_f32 v5, v12, v13
	ds_bpermute_b32 v7, v173, v6
	s_waitcnt lgkmcnt(0)
	v_add_f32_e32 v50, v6, v7
	v_mfma_f32_32x32x16_bf16 v[34:49], v[110:113], v[2:5], v[34:49]
	v_fmac_f32_e32 v50, v185, v52
	v_mfma_f32_32x32x16_bf16 v[58:73], v[106:109], v[2:5], v[58:73]

; DI void phase_attn_nsa(const Params& P, bf16_t* og, unsigned char* smem, int L, int G) {
;     ...
;       tot_addto(totL, tid, o0, o1, g1 / l);
;       tot_store(totL, tid, o0, o1, 1.f);
;     }
;     {
;       const bf16_t* kb = big + NS_KW + (size_t)b * SEQ * 256 + g * 64;
;       const bf16_t* vb = big + NS_VWT + (size_t)((b * 4 + g) * 64) * SEQ;
;       float m = NEGF, l = 0.f; o_zero(o0, o1);
;       const int jlo = (t0 - 511 > 0 ? t0 - 511 : 0) >> 6, jhi = (t0 + 31) >> 6;
;       KVR R; kv64_fetch(R, kb, 256, vb, SEQ, jlo * 64, true, tid);
;       __syncthreads();
;       kv64_store(R, sK, sVt, tid);
;       if (jlo < jhi) kv64_fetch(R, kb, 256, vb, SEQ, jlo * 64 + 64, true, tid);
.Lmy_nsasel_skip:
	s_mov_b64 s[100:101], exec
	s_mov_b64 exec, 1
	ds_write_b32 v252, v254
	s_mov_b64 exec, s[100:101]
	s_branch .LBB0_1355
.LBB0_1357:
	v_readlane_b32 s0, v246, 48
	v_readlane_b32 s1, v246, 49
	v_lshlrev_b32_e32 v0, 1, v187
	v_mov_b32_e32 v141, v1
	v_lshl_add_u64 v[34:35], v[144:145], 1, s[0:1]
	v_readlane_b32 s0, v246, 50
	v_readlane_b32 s1, v246, 51
	v_lshl_add_u64 v[34:35], v[34:35], 0, v[0:1]
	v_div_scale_f32 v72, vcc, v178, v185, v178
	v_lshl_add_u64 v[38:39], v[142:143], 1, s[0:1]
	s_max_i32 s0, s46, 0x1ff
	s_add_i32 s2, s0, 0xfffffe01
	s_and_b32 s44, s2, 0xffffffc0
	v_or_b32_e32 v0, s44, v169
	v_lshlrev_b64 v[36:37], 9, v[0:1]
	v_or_b32_e32 v0, s44, v174
	v_lshl_add_u64 v[36:37], v[34:35], 0, v[36:37]
	v_lshlrev_b64 v[40:41], 9, v[0:1]
	v_lshl_add_u64 v[36:37], v[36:37], 0, v[140:141]
	v_lshl_add_u64 v[40:41], v[34:35], 0, v[40:41]
	v_lshlrev_b32_e32 v0, 1, v186
	v_lshl_add_u64 v[40:41], v[40:41], 0, v[140:141]
	global_load_dwordx4 v[42:45], v[36:37], off
	global_load_dwordx4 v[46:49], v[40:41], off
	v_lshl_add_u64 v[36:37], v[38:39], 0, v[0:1]
	v_lshlrev_b32_e32 v0, 1, v184
	s_lshl_b64 s[0:1], s[44:45], 1
	v_lshl_add_u64 v[38:39], v[38:39], 0, v[0:1]
	v_lshl_add_u64 v[40:41], v[36:37], 0, s[0:1]
	v_lshl_add_u64 v[54:55], v[38:39], 0, s[0:1]
	v_lshl_add_u64 v[40:41], v[40:41], 0, v[140:141]
	v_lshl_add_u64 v[58:59], v[54:55], 0, v[140:141]
	global_load_dwordx4 v[50:53], v[40:41], off
	global_load_dwordx4 v[54:57], v[58:59], off
	v_div_scale_f32 v0, s[0:1], v185, v185, v178
	v_rcp_f32_e32 v73, v0
	ds_read_b128 v[60:63], v180 offset:37376
	ds_read_b128 v[64:67], v180 offset:41472
	ds_read_b128 v[68:71], v180 offset:53760
	s_waitcnt vmcnt(7)
	ds_read_b128 v[90:93], v180 offset:57856
	s_waitcnt vmcnt(6)
	ds_read_b128 v[94:97], v180 offset:45568
	s_waitcnt vmcnt(5)
	ds_read_b128 v[98:101], v180 offset:49664
	s_waitcnt vmcnt(4)
	ds_read_b128 v[102:105], v180 offset:61952
	ds_read_b128 v[106:109], v181 offset:28672
	s_lshr_b32 s2, s2, 6
	v_fma_f32 v110, -v0, v73, 1.0
	v_fmac_f32_e32 v73, v110, v73
	v_mul_f32_e32 v110, v72, v73
	v_fma_f32 v111, -v0, v110, v72
	v_fmac_f32_e32 v110, v111, v73
	v_fma_f32 v0, -v0, v110, v72
	v_div_fmas_f32 v0, v0, v73, v110
	v_div_fixup_f32 v0, v0, v185, v178
	s_waitcnt lgkmcnt(7)
	v_pk_fma_f32 v[18:19], v[0:1], v[18:19], v[60:61] op_sel_hi:[0,1,1]
	v_pk_fma_f32 v[20:21], v[0:1], v[20:21], v[62:63] op_sel_hi:[0,1,1]
	s_cmp_lt_u32 s2, s20
	s_waitcnt lgkmcnt(5)
	v_pk_fma_f32 v[2:3], v[0:1], v[2:3], v[68:69] op_sel_hi:[0,1,1]
	v_pk_fma_f32 v[4:5], v[0:1], v[4:5], v[70:71] op_sel_hi:[0,1,1]
	v_pk_fma_f32 v[22:23], v[0:1], v[22:23], v[64:65] op_sel_hi:[0,1,1]
	v_pk_fma_f32 v[24:25], v[0:1], v[24:25], v[66:67] op_sel_hi:[0,1,1]
	s_waitcnt lgkmcnt(4)
	v_pk_fma_f32 v[6:7], v[0:1], v[6:7], v[90:91] op_sel_hi:[0,1,1]
	v_pk_fma_f32 v[8:9], v[0:1], v[8:9], v[92:93] op_sel_hi:[0,1,1]
	s_waitcnt lgkmcnt(3)
	v_pk_fma_f32 v[26:27], v[0:1], v[26:27], v[94:95] op_sel_hi:[0,1,1]
	v_pk_fma_f32 v[28:29], v[0:1], v[28:29], v[96:97] op_sel_hi:[0,1,1]
	s_waitcnt lgkmcnt(1)
	v_pk_fma_f32 v[10:11], v[0:1], v[10:11], v[102:103] op_sel_hi:[0,1,1]
	v_pk_fma_f32 v[12:13], v[0:1], v[12:13], v[104:105] op_sel_hi:[0,1,1]
	v_pk_fma_f32 v[30:31], v[0:1], v[30:31], v[98:99] op_sel_hi:[0,1,1]
	v_pk_fma_f32 v[32:33], v[0:1], v[32:33], v[100:101] op_sel_hi:[0,1,1]
	s_waitcnt lgkmcnt(0)
	v_pk_fma_f32 v[14:15], v[0:1], v[14:15], v[106:107] op_sel_hi:[0,1,1]
	v_pk_fma_f32 v[16:17], v[0:1], v[16:17], v[108:109] op_sel_hi:[0,1,1]
	ds_write_b128 v180, v[18:21] offset:37376
	ds_write_b128 v180, v[2:5] offset:53760
	ds_write_b128 v180, v[22:25] offset:41472
	ds_write_b128 v180, v[6:9] offset:57856
	ds_write_b128 v180, v[26:29] offset:45568
	ds_write_b128 v180, v[10:13] offset:61952
	ds_write_b128 v180, v[30:33] offset:49664
	ds_write_b128 v181, v[14:17] offset:28672
	s_waitcnt lgkmcnt(0)
	v_lshrrev_b32_e32 v250, 8, v192
	v_bfe_u32 v252, v192, 6, 2
	v_and_b32_e32 v251, 7, v192
	v_lshlrev_b32_e32 v250, 6, v250
	v_lshl_add_u32 v252, v252, 2, v250
	v_lshl_add_u32 v250, v251, 2, v250
	v_add_u32_e32 v252, 0x24800, v252
	v_add_u32_e32 v250, 0x24800, v250
	v_mov_b32_e32 v254, 0
	s_mov_b32 s99, 0
	s_barrier
	s_mov_b64 s[100:101], exec
	s_mov_b64 exec, 1
	ds_write_b32 v252, v254
	ds_write_b32 v252, v254 offset:16
	s_mov_b64 exec, s[100:101]
	s_waitcnt vmcnt(3)
	ds_write_b128 v170, v[42:45]
	s_waitcnt vmcnt(2)
	ds_write_b128 v170, v[46:49] offset:4608
	s_waitcnt vmcnt(1)
	ds_write_b128 v170, v[50:53] offset:9216
	s_waitcnt vmcnt(0)
	ds_write_b128 v170, v[54:57] offset:13824
	s_cbranch_scc0 .LBB0_1359
	s_add_i32 s0, s44, 64
	v_or_b32_e32 v0, s0, v169
	v_lshlrev_b64 v[2:3], 9, v[0:1]
	v_or_b32_e32 v0, s0, v174
	v_lshl_add_u64 v[2:3], v[34:35], 0, v[2:3]
	v_lshlrev_b64 v[4:5], 9, v[0:1]
	v_lshl_add_u64 v[2:3], v[2:3], 0, v[140:141]
	v_lshl_add_u64 v[4:5], v[34:35], 0, v[4:5]
	v_lshl_add_u64 v[4:5], v[4:5], 0, v[140:141]
	global_load_dwordx4 v[42:45], v[2:3], off
	global_load_dwordx4 v[46:49], v[4:5], off
	global_load_dwordx4 v[50:53], v[40:41], off offset:128
	global_load_dwordx4 v[54:57], v[58:59], off offset:128

; DI void phase_attn_nsa(const Params& P, bf16_t* og, unsigned char* smem, int L, int G) {
;     ...
;       for (int j = jlo; j <= jhi; ++j) {
;         const int key0 = j * 64, cb = (j - jlo) & 1;
;         __syncthreads();
;         if (j < jhi) kv64_store(R, sK + (cb ^ 1) * KVB64, sVt + (cb ^ 1) * KVB64, tid);
;         if (j + 1 < jhi) kv64_fetch(R, kb, 256, vb, SEQ, key0 + 128, true, tid);
.LBB0_1361:
	s_add_i32 s0, s2, s4
	s_and_b32 s5, s4, 1
	s_add_i32 s98, s4, 1
	v_mov_b32_e32 v254, s98
	s_cmp_eq_u32 s4, 0
	s_cbranch_scc0 .Lmy_nsawin_spin
	s_waitcnt lgkmcnt(0)
	s_barrier
	v_readfirstlane_b32 s100, v192
	s_cmp_lt_u32 s100, 0x100
	s_cbranch_scc1 .Lmy_nsawin_go
	s_sleep 10
	s_branch .Lmy_nsawin_go
.Lmy_nsawin_spin:
	ds_read_b32 v251, v250
	s_waitcnt lgkmcnt(0)
	v_cmp_gt_u32_e32 vcc, s4, v251
	s_cbranch_vccz .Lmy_nsawin_go
	s_add_i32 s99, s99, 1
	s_cmp_lt_u32 s99, 0x2000
	s_cbranch_scc1 .Lmy_nsawin_spin
.Lmy_nsawin_go:
	s_cmp_ge_u32 s0, s20
	s_cbranch_scc1 .LBB0_1363
	s_xor_b32 s1, s5, 1
	s_mulk_i32 s1, 0x4800
	v_add_u32_e32 v0, s1, v170
	s_waitcnt vmcnt(3)
	ds_write_b128 v0, v[42:45]
	s_waitcnt vmcnt(2)
	ds_write_b128 v0, v[46:49] offset:4608
	s_waitcnt vmcnt(1)
	ds_write_b128 v0, v[50:53] offset:9216
	s_waitcnt vmcnt(0)
	ds_write_b128 v0, v[54:57] offset:13824
	s_mov_b64 s[100:101], exec
	s_mov_b64 exec, 1
	ds_write_b32 v252, v254 offset:16
	s_mov_b64 exec, s[100:101]

; #define MFMA(a, b, c) __builtin_amdgcn_mfma_f32_32x32x16_bf16((a), (b), (c), 0, 0, 0)
; template <int DQK, bool MASKED, int MODE, class MF>
; DI void attn_step(const bf16_t* sK, const bf16_t* sVt, const bf16x8 (&qf)[DQK / 16], f32x16& o0, f32x16& o1, float& m, float& l,
;                   float sc, const MF& mf, int lane, f32x16 (&s)[2], float invl, bool lanevalid = true) {
;     ...
; #pragma unroll
;   for (int sub = 0; sub < 2; ++sub)
; #pragma unroll
;     for (int ks = 0; ks < DQK / 16; ++ks) kf[sub][ks] = *(const bf16x8*)(sK + (sub * 32 + pr) * KST + ks * 16 + 8 * h);
;   __builtin_amdgcn_sched_barrier(0);
; #pragma unroll
;   for (int q = 0; q < 16; ++q) { s[0][q] = 0.f; s[1][q] = 0.f; }
; #pragma unroll
;   for (int ks = 0; ks < DQK / 16; ++ks) {
;     s[0] = MFMA(kf[0][ks], qf[ks], s[0]);
;     s[1] = MFMA(kf[1][ks], qf[ks], s[1]);
;   }
;   bf16x8 vf[2][2][2];
;   if (MODE != 1) {
; #pragma unroll
;     for (int sub = 0; sub < 2; ++sub)
; #pragma unroll
;       for (int s2 = 0; s2 < 2; ++s2) {
;         vf[sub][s2][0] = *(const bf16x8*)(sVt + r * 72 + sub * 32 + s2 * 16 + 8 * h);
;         vf[sub][s2][1] = *(const bf16x8*)(sVt + (32 + r) * 72 + sub * 32 + s2 * 16 + 8 * h);
;       }
;     __builtin_amdgcn_sched_barrier(0);
;   }
;   float mxr = -3.0e38f;
; #pragma unroll
;   for (int sub = 0; sub < 2; ++sub)
; #pragma unroll
;     for (int q = 0; q < 16; ++q) {
;       if (MASKED) { const int kk = sub * 32 + 16 * (q >> 3) + 8 * h + (q & 7); s[sub][q] = mf(kk) ? s[sub][q] : -3.0e38f; }
; DI void phase_attn_nsa(const Params& P, bf16_t* og, unsigned char* smem, int L, int G) {
;     ...
;         auto mf = [&](int kk) { const int key = key0 + kk; return key <= t && key > t - 512; };
;         if (key0 + 63 > t0 || key0 <= t0 + 31 - 512) attn_step<64, true, 0>(sK + cb * KVB64, sVt + cb * KVB64, qf, o0, o1, m, l, sc, mf, lane, s, 0.f);
.LBB0_1365:
	s_add_i32 s0, s44, 63
	s_cmp_le_u32 s0, s46
	s_cselect_b64 s[0:1], -1, 0
	s_cmp_gt_i32 s44, s3
	s_cselect_b64 s[6:7], -1, 0
	s_and_b64 s[6:7], s[0:1], s[6:7]
	s_mulk_i32 s5, 0x2400
	v_lshl_add_u32 v98, s5, 1, v153
	s_mov_b64 s[0:1], -1
	s_and_b64 vcc, exec, s[6:7]
	v_max_f32_e32 v149, v148, v148
	s_cbranch_vccnz .LBB0_1367
	v_lshl_add_u32 v0, s5, 1, v172
	ds_read_b128 v[2:5], v0
	ds_read_b128 v[34:37], v0 offset:32
	ds_read_b128 v[38:41], v0 offset:64
	ds_read_b128 v[58:61], v0 offset:96
	ds_read_b128 v[6:9], v0 offset:4608
	ds_read_b128 v[62:65], v0 offset:4640
	ds_read_b128 v[66:69], v0 offset:4672
	ds_read_b128 v[184:187], v0 offset:4704
	s_waitcnt lgkmcnt(7)
	v_mfma_f32_32x32x16_bf16 v[18:33], v[2:5], v[74:77], 0
	v_lshlrev_b32_e32 v0, 1, v171
	s_waitcnt lgkmcnt(3)
	v_mfma_f32_32x32x16_bf16 v[2:17], v[6:9], v[74:77], 0
	v_mfma_f32_32x32x16_bf16 v[18:33], v[34:37], v[78:81], v[18:33]
	v_add3_u32 v34, v98, v175, v0
	v_add3_u32 v0, v98, v177, v0
	s_waitcnt lgkmcnt(2)
	v_mfma_f32_32x32x16_bf16 v[2:17], v[62:65], v[78:81], v[2:17]
	v_mfma_f32_32x32x16_bf16 v[18:33], v[38:41], v[82:85], v[18:33]
	s_waitcnt lgkmcnt(1)
	v_mfma_f32_32x32x16_bf16 v[2:17], v[66:69], v[82:85], v[2:17]
	v_mfma_f32_32x32x16_bf16 v[18:33], v[58:61], v[86:89], v[18:33]
	ds_read_b128 v[94:97], v34 offset:9216
	ds_read_b128 v[70:73], v34 offset:9248
	ds_read_b128 v[90:93], v0 offset:9216
	ds_read_b128 v[66:69], v0 offset:9248
	ds_read_b128 v[62:65], v34 offset:9280
	ds_read_b128 v[38:41], v34 offset:9312
	ds_read_b128 v[58:61], v0 offset:9280
	ds_read_b128 v[34:37], v0 offset:9312
	s_waitcnt lgkmcnt(8)
	v_mfma_f32_32x32x16_bf16 v[2:17], v[184:187], v[86:89], v[2:17]
	v_add_u32_e32 v0, s44, v171
	v_cmp_le_u32_e32 vcc, v0, v136
	v_cmp_gt_i32_e64 s[0:1], v0, v146
	s_and_b64 vcc, vcc, s[0:1]
	v_cndmask_b32_e32 v18, v166, v18, vcc
	v_cmp_lt_u32_e32 vcc, v0, v136
	v_cmp_ge_i32_e64 s[0:1], v0, v146
	s_and_b64 vcc, vcc, s[0:1]
	v_add_u32_e32 v99, 2, v0
	v_cndmask_b32_e32 v19, v166, v19, vcc
	v_cmp_le_u32_e32 vcc, v99, v136
	v_cmp_gt_i32_e64 s[0:1], v99, v146
	s_and_b64 vcc, vcc, s[0:1]
	v_add_u32_e32 v99, 3, v0
	v_cndmask_b32_e32 v20, v166, v20, vcc
	v_cmp_le_u32_e32 vcc, v99, v136
	v_cmp_gt_i32_e64 s[0:1], v99, v146
	s_and_b64 vcc, vcc, s[0:1]
	v_add_u32_e32 v99, 4, v0
	v_cndmask_b32_e32 v21, v166, v21, vcc
	v_cmp_le_u32_e32 vcc, v99, v136
	v_cmp_gt_i32_e64 s[0:1], v99, v146
	s_and_b64 vcc, vcc, s[0:1]
	v_add_u32_e32 v99, 5, v0
	v_cndmask_b32_e32 v22, v166, v22, vcc
	v_cmp_le_u32_e32 vcc, v99, v136
	v_cmp_gt_i32_e64 s[0:1], v99, v146
	s_and_b64 vcc, vcc, s[0:1]
	v_add_u32_e32 v99, 6, v0
	v_cndmask_b32_e32 v23, v166, v23, vcc
	v_cmp_le_u32_e32 vcc, v99, v136
	v_cmp_gt_i32_e64 s[0:1], v99, v146
	v_add_u32_e32 v99, s44, v139
	s_and_b64 vcc, vcc, s[0:1]
	v_or_b32_e32 v100, 7, v99
	v_cndmask_b32_e32 v24, v166, v24, vcc
	v_cmp_le_u32_e32 vcc, v100, v136
	v_cmp_gt_i32_e64 s[0:1], v100, v146
	s_and_b64 vcc, vcc, s[0:1]
	v_add_u32_e32 v100, 16, v0
	v_cndmask_b32_e32 v25, v166, v25, vcc
	v_cmp_le_u32_e32 vcc, v100, v136
	v_cmp_gt_i32_e64 s[0:1], v100, v146
	s_and_b64 vcc, vcc, s[0:1]
	v_add_u32_e32 v100, 17, v0
	v_cndmask_b32_e32 v26, v166, v26, vcc
	v_cmp_le_u32_e32 vcc, v100, v136
	v_cmp_gt_i32_e64 s[0:1], v100, v146
	s_and_b64 vcc, vcc, s[0:1]
	v_add_u32_e32 v100, 18, v0
	v_cndmask_b32_e32 v27, v166, v27, vcc
	v_cmp_le_u32_e32 vcc, v100, v136
	v_cmp_gt_i32_e64 s[0:1], v100, v146
	s_and_b64 vcc, vcc, s[0:1]
	v_add_u32_e32 v100, 19, v0
	v_cndmask_b32_e32 v28, v166, v28, vcc
	v_cmp_le_u32_e32 vcc, v100, v136
	v_cmp_gt_i32_e64 s[0:1], v100, v146
	s_and_b64 vcc, vcc, s[0:1]
	v_add_u32_e32 v100, 20, v0
	v_cndmask_b32_e32 v29, v166, v29, vcc
	v_cmp_le_u32_e32 vcc, v100, v136
	v_cmp_gt_i32_e64 s[0:1], v100, v146
	s_and_b64 vcc, vcc, s[0:1]
	v_add_u32_e32 v100, 21, v0
	v_cndmask_b32_e32 v30, v166, v30, vcc
	v_cmp_le_u32_e32 vcc, v100, v136
	v_cmp_gt_i32_e64 s[0:1], v100, v146
	s_and_b64 vcc, vcc, s[0:1]
	v_add_u32_e32 v100, 22, v0
	v_cndmask_b32_e32 v31, v166, v31, vcc
	v_cmp_le_u32_e32 vcc, v100, v136
	v_cmp_gt_i32_e64 s[0:1], v100, v146
	s_and_b64 vcc, vcc, s[0:1]
	v_or_b32_e32 v100, 23, v99
	v_cndmask_b32_e32 v32, v166, v32, vcc
	v_cmp_le_u32_e32 vcc, v100, v136
	v_cmp_gt_i32_e64 s[0:1], v100, v146
	s_and_b64 vcc, vcc, s[0:1]
	v_add_u32_e32 v100, 32, v0
	v_cndmask_b32_e32 v33, v166, v33, vcc
	v_cmp_le_u32_e32 vcc, v100, v136
	v_cmp_gt_i32_e64 s[0:1], v100, v146
	s_and_b64 vcc, vcc, s[0:1]
	v_add_u32_e32 v100, 33, v0
	v_cndmask_b32_e32 v2, v166, v2, vcc
	v_cmp_le_u32_e32 vcc, v100, v136
	v_cmp_gt_i32_e64 s[0:1], v100, v146
	s_and_b64 vcc, vcc, s[0:1]
	v_add_u32_e32 v100, 34, v0
	v_cndmask_b32_e32 v3, v166, v3, vcc
	v_cmp_le_u32_e32 vcc, v100, v136
	v_cmp_gt_i32_e64 s[0:1], v100, v146
	s_and_b64 vcc, vcc, s[0:1]
	v_add_u32_e32 v100, 35, v0
	v_cndmask_b32_e32 v4, v166, v4, vcc
	v_cmp_le_u32_e32 vcc, v100, v136
	v_cmp_gt_i32_e64 s[0:1], v100, v146
	s_and_b64 vcc, vcc, s[0:1]
	v_add_u32_e32 v100, 36, v0
	v_cndmask_b32_e32 v5, v166, v5, vcc
	v_cmp_le_u32_e32 vcc, v100, v136
	v_cmp_gt_i32_e64 s[0:1], v100, v146
	s_and_b64 vcc, vcc, s[0:1]
	v_add_u32_e32 v100, 37, v0
	v_cndmask_b32_e32 v6, v166, v6, vcc
	v_cmp_le_u32_e32 vcc, v100, v136
	v_cmp_gt_i32_e64 s[0:1], v100, v146
	s_and_b64 vcc, vcc, s[0:1]
	v_add_u32_e32 v100, 38, v0
	v_cndmask_b32_e32 v7, v166, v7, vcc
	v_cmp_le_u32_e32 vcc, v100, v136
	v_cmp_gt_i32_e64 s[0:1], v100, v146
	s_and_b64 vcc, vcc, s[0:1]
	v_or_b32_e32 v100, 39, v99
	v_cndmask_b32_e32 v8, v166, v8, vcc
	v_cmp_le_u32_e32 vcc, v100, v136
	v_cmp_gt_i32_e64 s[0:1], v100, v146
	s_and_b64 vcc, vcc, s[0:1]
	v_add_u32_e32 v100, 48, v0
	v_cndmask_b32_e32 v9, v166, v9, vcc
; #define MFMA(a, b, c) __builtin_amdgcn_mfma_f32_32x32x16_bf16((a), (b), (c), 0, 0, 0)
; DI unsigned pack2(float a, float b) { f32x2_t v = {a, b}; bf16x2_t r = __builtin_convertvector(v, bf16x2_t); return __builtin_bit_cast(unsigned, r); }
; DI float fexp2(float x) { return __builtin_amdgcn_exp2f(x); }
; DI float shx(float v, int m) { return __shfl_xor(v, m, 64); }
; template <int DQK, bool MASKED, int MODE, class MF>
; DI void attn_step(const bf16_t* sK, const bf16_t* sVt, const bf16x8 (&qf)[DQK / 16], f32x16& o0, f32x16& o1, float& m, float& l,
;                   float sc, const MF& mf, int lane, f32x16 (&s)[2], float invl, bool lanevalid = true) {
;     ...
;       if (MASKED) { const int kk = sub * 32 + 16 * (q >> 3) + 8 * h + (q & 7); s[sub][q] = mf(kk) ? s[sub][q] : -3.0e38f; }
;       if (MODE != 2) mxr = fmaxf(mxr, s[sub][q]);
;     }
;   float alpha = 1.f;
;   if (MODE != 2) {
;     float mx = fmaxf(m, mxr * sc);
;     mx = fmaxf(mx, shx(mx, 32));
;     if (!MASKED) mx = lanevalid ? mx : m;
;     alpha = fexp2(m - mx);
;     m = mx;
;   }
;   const float moff = (!MASKED && !lanevalid) ? 1.0e30f : m;
;   float ps = 0.f;
; #pragma unroll
;   for (int sub = 0; sub < 2; ++sub)
; #pragma unroll
;     for (int q = 0; q < 16; ++q) {
;       float pv = fexp2(__builtin_fmaf(s[sub][q], sc, -moff));
;       if (MASKED && MODE != 0) pv = (s[sub][q] > -1.0e38f) ? pv : 0.f;
;       if (MODE == 2) pv *= invl;
;       s[sub][q] = pv;
;       ps += pv;
;     }
;   if (MODE != 2) {
;     ps += shx(ps, 32);
;     l = l * alpha + ps;
;   }
;   if (MODE == 1) return;
;   if (MODE == 0) {
; #pragma unroll
;     for (int q = 0; q < 16; ++q) { o0[q] *= alpha; o1[q] *= alpha; }
;   }
; #pragma unroll
;   for (int sub = 0; sub < 2; ++sub)
; #pragma unroll
;     for (int s2 = 0; s2 < 2; ++s2) {
;       union { bf16x8 v; unsigned u[4]; } pb;
; #pragma unroll
;       for (int e = 0; e < 4; ++e) pb.u[e] = pack2(s[sub][8 * s2 + 2 * e], s[sub][8 * s2 + 2 * e + 1]);
;       o0 = MFMA(vf[sub][s2][0], pb.v, o0);
;       o1 = MFMA(vf[sub][s2][1], pb.v, o1);
;     }
	v_cmp_le_u32_e32 vcc, v100, v136
	v_cmp_gt_i32_e64 s[0:1], v100, v146
	s_and_b64 vcc, vcc, s[0:1]
	v_add_u32_e32 v100, 49, v0
	v_cndmask_b32_e32 v10, v166, v10, vcc
	v_cmp_le_u32_e32 vcc, v100, v136
	v_cmp_gt_i32_e64 s[0:1], v100, v146
	s_and_b64 vcc, vcc, s[0:1]
	v_cndmask_b32_e32 v101, v166, v11, vcc
	v_add_u32_e32 v11, 50, v0
	v_cmp_le_u32_e32 vcc, v11, v136
	v_cmp_gt_i32_e64 s[0:1], v11, v146
	s_and_b64 vcc, vcc, s[0:1]
	v_add_u32_e32 v11, 51, v0
	v_cndmask_b32_e32 v150, v166, v12, vcc
	v_cmp_le_u32_e32 vcc, v11, v136
	v_cmp_gt_i32_e64 s[0:1], v11, v146
	s_and_b64 vcc, vcc, s[0:1]
	v_add_u32_e32 v11, 52, v0
	v_cndmask_b32_e32 v151, v166, v13, vcc
	v_cmp_le_u32_e32 vcc, v11, v136
	v_cmp_gt_i32_e64 s[0:1], v11, v146
	s_and_b64 vcc, vcc, s[0:1]
	v_add_u32_e32 v11, 53, v0
	v_cndmask_b32_e32 v174, v166, v14, vcc
	v_cmp_le_u32_e32 vcc, v11, v136
	v_cmp_gt_i32_e64 s[0:1], v11, v146
	s_and_b64 vcc, vcc, s[0:1]
	v_add_u32_e32 v0, 54, v0
	v_cndmask_b32_e32 v178, v166, v15, vcc
	v_cmp_le_u32_e32 vcc, v0, v136
	v_cmp_gt_i32_e64 s[0:1], v0, v146
	s_and_b64 vcc, vcc, s[0:1]
	v_or_b32_e32 v0, 55, v99
	v_cndmask_b32_e32 v183, v166, v16, vcc
	v_cmp_le_u32_e32 vcc, v0, v136
	v_cmp_gt_i32_e64 s[0:1], v0, v146
	v_max3_f32 v0, v18, s8, v19
	v_max3_f32 v0, v0, v20, v21
	v_max3_f32 v0, v0, v22, v23
	v_max3_f32 v0, v0, v24, v25
	v_max3_f32 v0, v0, v26, v27
	v_max3_f32 v0, v0, v28, v29
	v_max3_f32 v0, v0, v30, v31
	v_max3_f32 v0, v0, v32, v33
	v_max3_f32 v0, v0, v2, v3
	v_max3_f32 v0, v0, v4, v5
	v_max3_f32 v0, v0, v6, v7
	v_max3_f32 v0, v0, v8, v9
	v_max3_f32 v0, v0, v10, v101
	s_and_b64 vcc, vcc, s[0:1]
	v_max3_f32 v0, v0, v150, v151
	v_cndmask_b32_e32 v99, v166, v17, vcc
	v_max3_f32 v0, v0, v174, v178
	v_max3_f32 v0, v0, v183, v99
	v_mul_f32_e32 v0, 0x3e38aa3b, v0
	v_max_f32_e32 v0, v149, v0
	ds_bpermute_b32 v11, v173, v0
	s_mov_b64 s[0:1], 0
	s_waitcnt lgkmcnt(0)
	s_mov_b64 s[100:101], exec
	s_mov_b64 exec, 1
	ds_write_b32 v252, v254
	s_mov_b64 exec, s[100:101]
	v_max_f32_e32 v11, v11, v11
	v_max_f32_e32 v0, v0, v11
	v_fma_f32 v11, v18, s33, -v0
	v_exp_f32_e32 v18, v11
	v_fma_f32 v11, v19, s33, -v0
	v_exp_f32_e32 v19, v11
	v_fma_f32 v11, v20, s33, -v0
	v_exp_f32_e32 v20, v11
	v_fma_f32 v13, v21, s33, -v0
	v_exp_f32_e32 v21, v13
	v_fma_f32 v13, v22, s33, -v0
	v_add_f32_e32 v12, 0, v18
	v_exp_f32_e32 v22, v13
	v_fma_f32 v13, v23, s33, -v0
	v_add_f32_e32 v12, v19, v12
	v_exp_f32_e32 v23, v13
	v_fma_f32 v13, v24, s33, -v0
	v_add_f32_e32 v12, v20, v12
	v_exp_f32_e32 v24, v13
	v_fma_f32 v13, v25, s33, -v0
	v_add_f32_e32 v12, v21, v12
	v_exp_f32_e32 v25, v13
	v_fma_f32 v13, v26, s33, -v0
	v_add_f32_e32 v12, v22, v12
	v_exp_f32_e32 v188, v13
	v_fma_f32 v13, v27, s33, -v0
	v_add_f32_e32 v12, v23, v12
	v_exp_f32_e32 v189, v13
	v_fma_f32 v13, v28, s33, -v0
	v_add_f32_e32 v12, v24, v12
	v_exp_f32_e32 v190, v13
	v_fma_f32 v13, v29, s33, -v0
	v_add_f32_e32 v12, v25, v12
	v_exp_f32_e32 v191, v13
	v_fma_f32 v13, v30, s33, -v0
	v_add_f32_e32 v12, v188, v12
	v_exp_f32_e32 v194, v13
	v_fma_f32 v13, v31, s33, -v0
	v_add_f32_e32 v12, v189, v12
	v_exp_f32_e32 v195, v13
	v_fma_f32 v13, v32, s33, -v0
	v_add_f32_e32 v12, v190, v12
	v_exp_f32_e32 v196, v13
	v_fma_f32 v13, v33, s33, -v0
	v_add_f32_e32 v12, v191, v12
	v_exp_f32_e32 v197, v13
	v_fma_f32 v2, v2, s33, -v0
	v_add_f32_e32 v12, v194, v12
	v_exp_f32_e32 v198, v2
	v_fma_f32 v2, v3, s33, -v0
	v_add_f32_e32 v12, v195, v12
	v_exp_f32_e32 v199, v2
	v_fma_f32 v2, v4, s33, -v0
	v_add_f32_e32 v12, v196, v12
	v_exp_f32_e32 v200, v2
	v_fma_f32 v3, v5, s33, -v0
	v_add_f32_e32 v2, v197, v12
	v_exp_f32_e32 v201, v3
	v_fma_f32 v3, v6, s33, -v0
	v_add_f32_e32 v2, v198, v2
	v_exp_f32_e32 v202, v3
	v_fma_f32 v3, v7, s33, -v0
	v_add_f32_e32 v2, v199, v2
	v_exp_f32_e32 v203, v3
	v_fma_f32 v3, v8, s33, -v0
	v_add_f32_e32 v2, v200, v2
	v_exp_f32_e32 v204, v3
	v_sub_f32_e32 v11, v148, v0
	v_add_f32_e32 v2, v201, v2
	v_add_f32_e32 v2, v202, v2
	v_exp_f32_e32 v100, v11
	v_add_f32_e32 v2, v203, v2
	v_add_f32_e32 v205, v204, v2
	v_fma_f32 v2, v9, s33, -v0
	v_exp_f32_e32 v206, v2
	v_fma_f32 v2, v10, s33, -v0
	v_exp_f32_e32 v207, v2
	v_pk_mul_f32 v[16:17], v[144:145], v[100:101] op_sel_hi:[1,0]
	v_pk_mul_f32 v[14:15], v[140:141], v[100:101] op_sel_hi:[1,0]
	v_pk_mul_f32 v[12:13], v[132:133], v[100:101] op_sel_hi:[1,0]
	v_pk_mul_f32 v[10:11], v[130:131], v[100:101] op_sel_hi:[1,0]
	v_pk_mul_f32 v[8:9], v[128:129], v[100:101] op_sel_hi:[1,0]
	v_pk_mul_f32 v[6:7], v[126:127], v[100:101] op_sel_hi:[1,0]
	v_pk_mul_f32 v[4:5], v[124:125], v[100:101] op_sel_hi:[1,0]
	v_pk_mul_f32 v[2:3], v[122:123], v[100:101] op_sel_hi:[1,0]
	v_pk_mul_f32 v[32:33], v[142:143], v[100:101] op_sel_hi:[1,0]
	v_cvt_pk_bf16_f32 v184, v18, v19
	v_cvt_pk_bf16_f32 v185, v20, v21
	v_cvt_pk_bf16_f32 v186, v22, v23
	v_cvt_pk_bf16_f32 v187, v24, v25
	v_pk_mul_f32 v[30:31], v[120:121], v[100:101] op_sel_hi:[1,0]
	v_pk_mul_f32 v[28:29], v[118:119], v[100:101] op_sel_hi:[1,0]
	v_pk_mul_f32 v[26:27], v[116:117], v[100:101] op_sel_hi:[1,0]
	v_pk_mul_f32 v[24:25], v[114:115], v[100:101] op_sel_hi:[1,0]
	v_pk_mul_f32 v[22:23], v[112:113], v[100:101] op_sel_hi:[1,0]
	v_pk_mul_f32 v[20:21], v[110:111], v[100:101] op_sel_hi:[1,0]
	v_pk_mul_f32 v[18:19], v[108:109], v[100:101] op_sel_hi:[1,0]
	v_mfma_f32_32x32x16_bf16 v[2:17], v[94:97], v[184:187], v[2:17]
	v_fma_f32 v95, v101, s33, -v0
	v_mfma_f32_32x32x16_bf16 v[18:33], v[90:93], v[184:187], v[18:33]
	v_add_f32_e32 v90, v206, v205
	v_add_f32_e32 v94, v207, v90
	v_cvt_pk_bf16_f32 v90, v188, v189
	v_cvt_pk_bf16_f32 v91, v190, v191
	v_cvt_pk_bf16_f32 v92, v194, v195
	v_cvt_pk_bf16_f32 v93, v196, v197
	s_nop 1
	v_mfma_f32_32x32x16_bf16 v[2:17], v[70:73], v[90:93], v[2:17]
	v_exp_f32_e32 v70, v95
	v_fma_f32 v71, v150, s33, -v0
	v_exp_f32_e32 v71, v71
	v_fma_f32 v72, v151, s33, -v0
	v_exp_f32_e32 v72, v72
	v_add_f32_e32 v73, v70, v94
	v_add_f32_e32 v73, v71, v73
	v_mfma_f32_32x32x16_bf16 v[18:33], v[66:69], v[90:93], v[18:33]
	v_fma_f32 v66, v174, s33, -v0
	v_exp_f32_e32 v90, v66
	v_cvt_pk_bf16_f32 v66, v198, v199
	v_cvt_pk_bf16_f32 v67, v200, v201
	v_cvt_pk_bf16_f32 v68, v202, v203
	v_cvt_pk_bf16_f32 v69, v204, v206
	v_add_f32_e32 v73, v72, v73
	s_nop 0
	v_mfma_f32_32x32x16_bf16 v[2:17], v[62:65], v[66:69], v[2:17]
	v_fma_f32 v63, v178, s33, -v0
	v_exp_f32_e32 v63, v63
	v_fma_f32 v64, v183, s33, -v0
	v_exp_f32_e32 v64, v64
	v_fma_f32 v65, v99, s33, -v0
	v_exp_f32_e32 v65, v65
	v_add_f32_e32 v62, v90, v73
	v_mfma_f32_32x32x16_bf16 v[18:33], v[58:61], v[66:69], v[18:33]
	v_add_f32_e32 v58, v63, v62
	v_add_f32_e32 v58, v64, v58
	v_add_f32_e32 v62, v65, v58
	v_cvt_pk_bf16_f32 v58, v207, v70
	v_cvt_pk_bf16_f32 v59, v71, v72
	v_cvt_pk_bf16_f32 v60, v90, v63
	v_cvt_pk_bf16_f32 v61, v64, v65
	s_nop 1
	v_mfma_f32_32x32x16_bf16 v[2:17], v[38:41], v[58:61], v[2:17]
	ds_bpermute_b32 v38, v173, v62
	s_waitcnt lgkmcnt(0)
	v_add_f32_e32 v40, v62, v38
	v_fmac_f32_e32 v40, v147, v100
	v_mfma_f32_32x32x16_bf16 v[18:33], v[34:37], v[58:61], v[18:33]
; template <int DQK, bool MASKED, int MODE, class MF>
; DI void attn_step(const bf16_t* sK, const bf16_t* sVt, const bf16x8 (&qf)[DQK / 16], f32x16& o0, f32x16& o1, float& m, float& l,
;                   float sc, const MF& mf, int lane, f32x16 (&s)[2], float invl, bool lanevalid = true) {
;     ...
; #pragma unroll
;   for (int sub = 0; sub < 2; ++sub)
; #pragma unroll
;     for (int ks = 0; ks < DQK / 16; ++ks) kf[sub][ks] = *(const bf16x8*)(sK + (sub * 32 + pr) * KST + ks * 16 + 8 * h);
;   __builtin_amdgcn_sched_barrier(0);
; #pragma unroll
;   for (int q = 0; q < 16; ++q) { s[0][q] = 0.f; s[1][q] = 0.f; }
; #pragma unroll
;   for (int ks = 0; ks < DQK / 16; ++ks) {
;     s[0] = MFMA(kf[0][ks], qf[ks], s[0]);
;     s[1] = MFMA(kf[1][ks], qf[ks], s[1]);
;   }
;   bf16x8 vf[2][2][2];
;   if (MODE != 1) {
; #pragma unroll
;     for (int sub = 0; sub < 2; ++sub)
; #pragma unroll
;       for (int s2 = 0; s2 < 2; ++s2) {
;         vf[sub][s2][0] = *(const bf16x8*)(sVt + r * 72 + sub * 32 + s2 * 16 + 8 * h);
;         vf[sub][s2][1] = *(const bf16x8*)(sVt + (32 + r) * 72 + sub * 32 + s2 * 16 + 8 * h);
;       }
;     __builtin_amdgcn_sched_barrier(0);
;   }
;   float mxr = -3.0e38f;
; #pragma unroll
;   for (int sub = 0; sub < 2; ++sub)
; #pragma unroll
;     for (int q = 0; q < 16; ++q) {
;       if (MASKED) { const int kk = sub * 32 + 16 * (q >> 3) + 8 * h + (q & 7); s[sub][q] = mf(kk) ? s[sub][q] : -3.0e38f; }
;       if (MODE != 2) mxr = fmaxf(mxr, s[sub][q]);
;     }
;   float alpha = 1.f;
;   if (MODE != 2) {
;     float mx = fmaxf(m, mxr * sc);
;     mx = fmaxf(mx, shx(mx, 32));
;     if (!MASKED) mx = lanevalid ? mx : m;
;     alpha = fexp2(m - mx);
;     m = mx;
;   }
;   const float moff = (!MASKED && !lanevalid) ? 1.0e30f : m;
;   float ps = 0.f;
; #pragma unroll
;   for (int sub = 0; sub < 2; ++sub)
; #pragma unroll
;     for (int q = 0; q < 16; ++q) {
;       float pv = fexp2(__builtin_fmaf(s[sub][q], sc, -moff));
;       if (MASKED && MODE != 0) pv = (s[sub][q] > -1.0e38f) ? pv : 0.f;
;       if (MODE == 2) pv *= invl;
;       s[sub][q] = pv;
;       ps += pv;
;     }
;   if (MODE != 2) {
;     ps += shx(ps, 32);
;     l = l * alpha + ps;
;   }
;   if (MODE == 1) return;
;   if (MODE == 0) {
; #pragma unroll
;     for (int q = 0; q < 16; ++q) { o0[q] *= alpha; o1[q] *= alpha; }
;   }
; #pragma unroll
;   for (int sub = 0; sub < 2; ++sub)
; #pragma unroll
.LBB0_1367:
	s_andn2_b64 vcc, exec, s[0:1]
	s_cbranch_vccnz .LBB0_1369
	v_lshl_add_u32 v0, s5, 1, v182
	s_nop 3
	ds_read_b128 v[2:5], v0
	s_nop 3
	ds_read_b128 v[18:21], v0 offset:32
	ds_read_b128 v[22:25], v0 offset:64
	ds_read_b128 v[58:61], v0 offset:96
	ds_read_b128 v[26:29], v0 offset:4608
	ds_read_b128 v[62:65], v0 offset:4640
	ds_read_b128 v[66:69], v0 offset:4672
	ds_read_b128 v[184:187], v0 offset:4704
	s_waitcnt lgkmcnt(7)
	v_mfma_f32_32x32x16_bf16 v[2:17], v[2:5], v[74:77], 0
	v_add3_u32 v0, v98, v175, v138
	s_waitcnt lgkmcnt(3)
	v_mfma_f32_32x32x16_bf16 v[26:41], v[26:29], v[74:77], 0
	v_mfma_f32_32x32x16_bf16 v[2:17], v[18:21], v[78:81], v[2:17]
	s_waitcnt lgkmcnt(2)
	v_mfma_f32_32x32x16_bf16 v[26:41], v[62:65], v[78:81], v[26:41]
	v_mfma_f32_32x32x16_bf16 v[2:17], v[22:25], v[82:85], v[2:17]
	v_add3_u32 v22, v98, v177, v138
	s_waitcnt lgkmcnt(1)
	v_mfma_f32_32x32x16_bf16 v[26:41], v[66:69], v[82:85], v[26:41]
	v_mfma_f32_32x32x16_bf16 v[2:17], v[58:61], v[86:89], v[2:17]
	ds_read_b128 v[18:21], v0 offset:9216
	ds_read_b128 v[94:97], v0 offset:9248
	ds_read_b128 v[98:101], v22 offset:9216
	ds_read_b128 v[90:93], v22 offset:9248
	ds_read_b128 v[70:73], v0 offset:9280
	ds_read_b128 v[62:65], v0 offset:9312
	ds_read_b128 v[66:69], v22 offset:9280
	ds_read_b128 v[58:61], v22 offset:9312
	s_waitcnt lgkmcnt(8)
	v_mfma_f32_32x32x16_bf16 v[26:41], v[184:187], v[86:89], v[26:41]
	s_nop 1
	v_max3_f32 v0, v2, s8, v3
	v_max3_f32 v0, v0, v4, v5
	v_max3_f32 v0, v0, v6, v7
	v_max3_f32 v0, v0, v8, v9
	v_max3_f32 v0, v0, v10, v11
	v_max3_f32 v0, v0, v12, v13
	v_max3_f32 v0, v0, v14, v15
	v_max3_f32 v0, v0, v16, v17
	s_nop 1
	v_max3_f32 v0, v0, v26, v27
	v_max3_f32 v0, v0, v28, v29
	v_max3_f32 v0, v0, v30, v31
	v_max3_f32 v0, v0, v32, v33
	v_max3_f32 v0, v0, v34, v35
	v_max3_f32 v0, v0, v36, v37
	v_max3_f32 v0, v0, v38, v39
	v_max3_f32 v0, v0, v40, v41
	v_mul_f32_e32 v0, 0x3e38aa3b, v0
	v_max_f32_e32 v0, v149, v0
	ds_bpermute_b32 v22, v173, v0
	s_waitcnt lgkmcnt(0)
	s_mov_b64 s[100:101], exec
	s_mov_b64 exec, 1
	ds_write_b32 v252, v254
	s_mov_b64 exec, s[100:101]
	v_max_f32_e32 v22, v22, v22
	v_max_f32_e32 v0, v0, v22
	v_fma_f32 v2, v2, s33, -v0
	v_fma_f32 v3, v3, s33, -v0
	v_exp_f32_e32 v23, v2
	v_fma_f32 v4, v4, s33, -v0
	v_exp_f32_e32 v24, v3
	v_fma_f32 v5, v5, s33, -v0
	v_exp_f32_e32 v25, v4
	v_exp_f32_e32 v149, v5
	v_fma_f32 v3, v6, s33, -v0
	v_add_f32_e32 v2, 0, v23
	v_exp_f32_e32 v150, v3
	v_fma_f32 v3, v7, s33, -v0
	v_add_f32_e32 v2, v24, v2
	v_exp_f32_e32 v151, v3
	v_fma_f32 v3, v8, s33, -v0
	v_add_f32_e32 v2, v25, v2
	v_exp_f32_e32 v174, v3
	v_fma_f32 v3, v9, s33, -v0
	v_add_f32_e32 v2, v149, v2
	v_exp_f32_e32 v178, v3
	v_fma_f32 v3, v10, s33, -v0
	v_add_f32_e32 v2, v150, v2
	v_exp_f32_e32 v183, v3
	v_fma_f32 v3, v11, s33, -v0
	v_add_f32_e32 v2, v151, v2
	v_exp_f32_e32 v184, v3
	v_fma_f32 v3, v12, s33, -v0
	v_add_f32_e32 v2, v174, v2
	v_exp_f32_e32 v185, v3
	v_fma_f32 v3, v13, s33, -v0
	v_add_f32_e32 v2, v178, v2
	v_exp_f32_e32 v186, v3
	v_fma_f32 v3, v14, s33, -v0
	v_add_f32_e32 v2, v183, v2
	v_exp_f32_e32 v187, v3
	v_fma_f32 v3, v15, s33, -v0
	v_add_f32_e32 v2, v184, v2
	v_exp_f32_e32 v188, v3
	v_fma_f32 v3, v16, s33, -v0
	v_add_f32_e32 v2, v185, v2
	v_exp_f32_e32 v189, v3
	v_fma_f32 v3, v17, s33, -v0
	v_add_f32_e32 v2, v186, v2
	v_exp_f32_e32 v190, v3
	v_fma_f32 v3, v26, s33, -v0
	v_add_f32_e32 v2, v187, v2
	v_exp_f32_e32 v191, v3
	v_fma_f32 v3, v27, s33, -v0
	v_add_f32_e32 v2, v188, v2
	v_exp_f32_e32 v194, v3
	v_fma_f32 v3, v28, s33, -v0
	v_add_f32_e32 v2, v189, v2
	v_exp_f32_e32 v195, v3
	v_fma_f32 v3, v29, s33, -v0
	v_add_f32_e32 v2, v190, v2
	v_exp_f32_e32 v196, v3
	v_fma_f32 v3, v30, s33, -v0
	v_add_f32_e32 v2, v191, v2
	v_exp_f32_e32 v197, v3
	v_fma_f32 v3, v31, s33, -v0
	v_add_f32_e32 v2, v194, v2
	v_exp_f32_e32 v198, v3
	v_fma_f32 v3, v32, s33, -v0
	v_add_f32_e32 v2, v195, v2
	v_exp_f32_e32 v199, v3
	v_sub_f32_e32 v22, v148, v0
	v_add_f32_e32 v2, v196, v2
	v_add_f32_e32 v2, v197, v2
	v_exp_f32_e32 v148, v22
	v_add_f32_e32 v2, v198, v2
	v_add_f32_e32 v200, v199, v2
	v_fma_f32 v2, v33, s33, -v0
	v_exp_f32_e32 v201, v2
	v_fma_f32 v2, v34, s33, -v0
	v_exp_f32_e32 v202, v2
	v_pk_mul_f32 v[16:17], v[144:145], v[148:149] op_sel_hi:[1,0]
	v_pk_mul_f32 v[14:15], v[140:141], v[148:149] op_sel_hi:[1,0]
	v_pk_mul_f32 v[12:13], v[132:133], v[148:149] op_sel_hi:[1,0]
	v_pk_mul_f32 v[10:11], v[130:131], v[148:149] op_sel_hi:[1,0]
	v_pk_mul_f32 v[8:9], v[128:129], v[148:149] op_sel_hi:[1,0]
	v_pk_mul_f32 v[6:7], v[126:127], v[148:149] op_sel_hi:[1,0]
	v_pk_mul_f32 v[4:5], v[124:125], v[148:149] op_sel_hi:[1,0]
	v_pk_mul_f32 v[2:3], v[122:123], v[148:149] op_sel_hi:[1,0]
	v_cvt_pk_bf16_f32 v122, v23, v24
	v_cvt_pk_bf16_f32 v123, v25, v149
	v_cvt_pk_bf16_f32 v124, v150, v151
	v_cvt_pk_bf16_f32 v125, v174, v178
	v_pk_mul_f32 v[32:33], v[142:143], v[148:149] op_sel_hi:[1,0]
	v_pk_mul_f32 v[30:31], v[120:121], v[148:149] op_sel_hi:[1,0]
	v_mfma_f32_32x32x16_bf16 v[2:17], v[18:21], v[122:125], v[2:17]
	v_mul_f32_e64 v28, v118, v148
	v_mul_f32_e64 v29, v119, v148
	v_mul_f32_e64 v26, v116, v148
	v_mul_f32_e64 v27, v117, v148
	v_mul_f32_e64 v24, v114, v148
	v_mul_f32_e64 v25, v115, v148
	v_pk_mul_f32 v[22:23], v[112:113], v[148:149] op_sel_hi:[1,0]
	v_pk_mul_f32 v[20:21], v[110:111], v[148:149] op_sel_hi:[1,0]
	v_pk_mul_f32 v[18:19], v[108:109], v[148:149] op_sel_hi:[1,0]
	v_fma_f32 v35, v35, s33, -v0
	v_add_f32_e32 v34, v201, v200
	v_mfma_f32_32x32x16_bf16 v[18:33], v[98:101], v[122:125], v[18:33]
	v_cvt_pk_bf16_f32 v98, v183, v184
	v_cvt_pk_bf16_f32 v99, v185, v186
	v_cvt_pk_bf16_f32 v100, v187, v188
	v_cvt_pk_bf16_f32 v101, v189, v190
	v_add_f32_e32 v34, v202, v34
	v_fma_f32 v39, v39, s33, -v0
	v_exp_f32_e32 v39, v39
	v_mfma_f32_32x32x16_bf16 v[2:17], v[94:97], v[98:101], v[2:17]
	v_exp_f32_e32 v94, v35
	v_fma_f32 v35, v36, s33, -v0
	v_exp_f32_e32 v95, v35
	v_fma_f32 v35, v37, s33, -v0
	v_exp_f32_e32 v96, v35
	v_add_f32_e32 v34, v94, v34
	v_add_f32_e32 v34, v95, v34
	v_mfma_f32_32x32x16_bf16 v[18:33], v[90:93], v[98:101], v[18:33]
	v_add_f32_e32 v90, v96, v34
	v_fma_f32 v34, v38, s33, -v0
	v_exp_f32_e32 v38, v34
	v_cvt_pk_bf16_f32 v34, v191, v194
	v_cvt_pk_bf16_f32 v35, v195, v196
	v_cvt_pk_bf16_f32 v36, v197, v198
	v_cvt_pk_bf16_f32 v37, v199, v201
	v_fma_f32 v40, v40, s33, -v0
	v_exp_f32_e32 v40, v40
	v_mfma_f32_32x32x16_bf16 v[2:17], v[70:73], v[34:37], v[2:17]
	v_fma_f32 v41, v41, s33, -v0
	v_exp_f32_e32 v41, v41
	v_add_f32_e32 v70, v38, v90
	v_mfma_f32_32x32x16_bf16 v[18:33], v[66:69], v[34:37], v[18:33]
	v_add_f32_e32 v34, v39, v70
	v_add_f32_e32 v34, v40, v34
	v_add_f32_e32 v66, v41, v34
	v_cvt_pk_bf16_f32 v34, v202, v94
	v_cvt_pk_bf16_f32 v35, v95, v96
	v_cvt_pk_bf16_f32 v36, v38, v39
	v_cvt_pk_bf16_f32 v37, v40, v41
	ds_bpermute_b32 v38, v173, v66
	s_waitcnt lgkmcnt(0)
	v_add_f32_e32 v40, v66, v38
	v_mfma_f32_32x32x16_bf16 v[2:17], v[62:65], v[34:37], v[2:17]
	v_fmac_f32_e32 v40, v147, v148
	v_mfma_f32_32x32x16_bf16 v[18:33], v[58:61], v[34:37], v[18:33]
